# baseline (speedup 1.0000x reference)
; template <int N, int K, int EPI>
; __device__ void gemm_phase(const u16* __restrict__ A, const u16* __restrict__ Bt, const EpiArgs ea, char* smem, int tid) {
;     ...
;     for (int t = 0; t < nt; t += 2) {
;       const bool lastit = (t == nt - 2);
;       const u16* A2 = lastit ? Abn : Ab;
;       const u16* B2 = lastit ? Bbn : Bb;
;       const int k2 = lastit ? 0 : t + 2;
;       BODY(Ab, t + 1, A2, B2, k2, k2 + 1);
.LBB0_64:
	ds_read_b128 v[142:145], v135
	ds_read_b128 v[166:169], v139
	ds_read_b128 v[170:173], v135 offset:2048
	ds_read_b128 v[174:177], v139 offset:2048
	s_add_u32 s18, s16, 0x40080
	s_addc_u32 s19, s17, 0
	s_add_u32 s20, s16, 0x60080
	s_addc_u32 s21, s17, 0
	s_cmp_eq_u32 s3, 12
	s_cselect_b32 vcc_lo, s11, s15
	s_cselect_b32 vcc_hi, s10, s14
	s_cselect_b32 s82, s9, s13
	s_cselect_b32 s83, s8, s12
	s_nop 0
	ds_read_b128 v[178:181], v136
	ds_read_b128 v[182:185], v137
	ds_read_b128 v[186:189], v136 offset:2048
	ds_read_b128 v[190:193], v137 offset:2048
	ds_read_b128 v[194:197], v136 offset:4096
	ds_read_b128 v[198:201], v137 offset:4096
	ds_read_b128 v[202:205], v136 offset:6144
	ds_read_b128 v[206:209], v137 offset:6144
	s_mov_b32 m0, s72
	s_nop 0
	global_load_lds_dwordx4 v130, s[18:19]
	s_nop 0
	s_mov_b32 m0, s73
	s_nop 0
	global_load_lds_dwordx4 v130, s[20:21]
	ds_read_b128 v[210:213], v135 offset:16384
	ds_read_b128 v[214:217], v139 offset:16384
	ds_read_b128 v[218:221], v135 offset:18432
	ds_read_b128 v[222:225], v139 offset:18432
	s_waitcnt vmcnt(8) lgkmcnt(0)
	s_barrier
	s_waitcnt lgkmcnt(7)
	v_mfma_f32_16x16x32_bf16 v[124:127], v[142:145], v[178:181], v[124:127]
	v_mfma_f32_16x16x32_bf16 v[120:123], v[170:173], v[178:181], v[120:123]
	s_waitcnt lgkmcnt(5)
	v_mfma_f32_16x16x32_bf16 v[88:91], v[218:221], v[178:181], v[88:91]
	v_mfma_f32_16x16x32_bf16 v[92:95], v[210:213], v[178:181], v[92:95]
	s_waitcnt lgkmcnt(3)
	v_mfma_f32_16x16x32_bf16 v[84:87], v[210:213], v[186:189], v[84:87]
	v_mfma_f32_16x16x32_bf16 v[80:83], v[218:221], v[186:189], v[80:83]
	s_waitcnt lgkmcnt(1)
	v_mfma_f32_16x16x32_bf16 v[112:115], v[170:173], v[186:189], v[112:115]
	v_mfma_f32_16x16x32_bf16 v[116:119], v[142:145], v[186:189], v[116:119]
	v_mfma_f32_16x16x32_bf16 v[108:111], v[142:145], v[194:197], v[108:111]
	v_mfma_f32_16x16x32_bf16 v[104:107], v[170:173], v[194:197], v[104:107]
	v_mfma_f32_16x16x32_bf16 v[72:75], v[218:221], v[194:197], v[72:75]
	v_mfma_f32_16x16x32_bf16 v[76:79], v[210:213], v[194:197], v[76:79]
	v_mfma_f32_16x16x32_bf16 v[68:71], v[210:213], v[202:205], v[68:71]
	v_mfma_f32_16x16x32_bf16 v[64:67], v[218:221], v[202:205], v[64:67]
	s_waitcnt lgkmcnt(0)
	v_mfma_f32_16x16x32_bf16 v[96:99], v[170:173], v[202:205], v[96:99]
	v_mfma_f32_16x16x32_bf16 v[100:103], v[142:145], v[202:205], v[100:103]
	s_waitcnt lgkmcnt(3)
	v_mfma_f32_16x16x32_bf16 v[100:103], v[166:169], v[206:209], v[100:103]
	s_waitcnt lgkmcnt(1)
	v_mfma_f32_16x16x32_bf16 v[96:99], v[174:177], v[206:209], v[96:99]
	v_mfma_f32_16x16x32_bf16 v[64:67], v[222:225], v[206:209], v[64:67]
	v_mfma_f32_16x16x32_bf16 v[68:71], v[214:217], v[206:209], v[68:71]
	v_mfma_f32_16x16x32_bf16 v[76:79], v[214:217], v[198:201], v[76:79]
	v_mfma_f32_16x16x32_bf16 v[72:75], v[222:225], v[198:201], v[72:75]
	v_mfma_f32_16x16x32_bf16 v[104:107], v[174:177], v[198:201], v[104:107]
	v_mfma_f32_16x16x32_bf16 v[108:111], v[166:169], v[198:201], v[108:111]
	v_mfma_f32_16x16x32_bf16 v[116:119], v[166:169], v[190:193], v[116:119]
	s_waitcnt lgkmcnt(0)
	v_mfma_f32_16x16x32_bf16 v[112:115], v[174:177], v[190:193], v[112:115]
	v_mfma_f32_16x16x32_bf16 v[80:83], v[222:225], v[190:193], v[80:83]
	v_mfma_f32_16x16x32_bf16 v[84:87], v[214:217], v[190:193], v[84:87]
	v_mfma_f32_16x16x32_bf16 v[92:95], v[214:217], v[182:185], v[92:95]
	v_mfma_f32_16x16x32_bf16 v[88:91], v[222:225], v[182:185], v[88:91]
	v_mfma_f32_16x16x32_bf16 v[120:123], v[174:177], v[182:185], v[120:123]
	v_mfma_f32_16x16x32_bf16 v[124:127], v[166:169], v[182:185], v[124:127]
	s_barrier
	s_cselect_b32 s70, 0, s5
	s_lshl_b64 s[92:93], s[70:71], 1
	s_add_u32 s18, vcc_hi, s92
	s_addc_u32 s19, vcc_lo, s93
	s_add_u32 s20, s18, 0x20000
	s_mov_b32 m0, s26
	s_nop 0
	global_load_lds_dwordx4 v130, s[18:19]
	s_addc_u32 s21, s19, 0
	s_mov_b32 m0, s27
	s_nop 0
	global_load_lds_dwordx4 v130, s[20:21]
	ds_read_b128 v[178:181], v136 offset:16384
	ds_read_b128 v[182:185], v137 offset:16384
	ds_read_b128 v[186:189], v136 offset:18432
	ds_read_b128 v[190:193], v137 offset:18432
	ds_read_b128 v[194:197], v136 offset:20480
	ds_read_b128 v[198:201], v137 offset:20480
	ds_read_b128 v[202:205], v136 offset:22528
	ds_read_b128 v[206:209], v137 offset:22528
	s_add_u32 s20, s83, s92
	s_addc_u32 s21, s82, s93
	s_add_u32 s82, s20, 0x20000
	s_mov_b32 m0, s25
	s_nop 0
	global_load_lds_dwordx4 v130, s[20:21]
	s_addc_u32 s83, s21, 0
	s_mov_b32 m0, s28
	s_nop 0
	global_load_lds_dwordx4 v130, s[82:83]
	s_add_u32 vcc_hi, vcc_hi, 0x40000
	s_addc_u32 vcc_lo, vcc_lo, 0
	s_add_u32 s82, vcc_hi, s92
	s_addc_u32 s83, vcc_lo, s93
	s_add_u32 s92, s82, 0x20000
	s_mov_b32 m0, s29
	s_nop 0
	global_load_lds_dwordx4 v130, s[82:83]
	s_addc_u32 s93, s83, 0
	s_mov_b32 m0, s30
	s_nop 0
	global_load_lds_dwordx4 v130, s[92:93]
	s_waitcnt vmcnt(8) lgkmcnt(0)
	s_barrier
	s_waitcnt lgkmcnt(7)
	v_mfma_f32_16x16x32_bf16 v[60:63], v[142:145], v[178:181], v[60:63]
	v_mfma_f32_16x16x32_bf16 v[56:59], v[170:173], v[178:181], v[56:59]
	s_waitcnt lgkmcnt(5)
	v_mfma_f32_16x16x32_bf16 v[24:27], v[218:221], v[178:181], v[24:27]
	v_mfma_f32_16x16x32_bf16 v[28:31], v[210:213], v[178:181], v[28:31]
	s_waitcnt lgkmcnt(3)
	v_mfma_f32_16x16x32_bf16 v[20:23], v[210:213], v[186:189], v[20:23]
	v_mfma_f32_16x16x32_bf16 v[16:19], v[218:221], v[186:189], v[16:19]
	s_waitcnt lgkmcnt(1)
	v_mfma_f32_16x16x32_bf16 v[48:51], v[170:173], v[186:189], v[48:51]
	v_mfma_f32_16x16x32_bf16 v[52:55], v[142:145], v[186:189], v[52:55]
	v_mfma_f32_16x16x32_bf16 v[44:47], v[142:145], v[194:197], v[44:47]
	v_mfma_f32_16x16x32_bf16 v[40:43], v[170:173], v[194:197], v[40:43]
	v_mfma_f32_16x16x32_bf16 v[8:11], v[218:221], v[194:197], v[8:11]
	v_mfma_f32_16x16x32_bf16 v[12:15], v[210:213], v[194:197], v[12:15]
	v_mfma_f32_16x16x32_bf16 v[4:7], v[210:213], v[202:205], v[4:7]
	v_mfma_f32_16x16x32_bf16 v[0:3], v[218:221], v[202:205], v[0:3]
	s_waitcnt lgkmcnt(0)
	v_mfma_f32_16x16x32_bf16 v[32:35], v[170:173], v[202:205], v[32:35]
	v_mfma_f32_16x16x32_bf16 v[36:39], v[142:145], v[202:205], v[36:39]
	v_mfma_f32_16x16x32_bf16 v[36:39], v[166:169], v[206:209], v[36:39]
	v_mfma_f32_16x16x32_bf16 v[32:35], v[174:177], v[206:209], v[32:35]
	v_mfma_f32_16x16x32_bf16 v[0:3], v[222:225], v[206:209], v[0:3]
	v_mfma_f32_16x16x32_bf16 v[4:7], v[214:217], v[206:209], v[4:7]
	v_mfma_f32_16x16x32_bf16 v[12:15], v[214:217], v[198:201], v[12:15]
	v_mfma_f32_16x16x32_bf16 v[8:11], v[222:225], v[198:201], v[8:11]
	v_mfma_f32_16x16x32_bf16 v[40:43], v[174:177], v[198:201], v[40:43]
	v_mfma_f32_16x16x32_bf16 v[44:47], v[166:169], v[198:201], v[44:47]
	v_mfma_f32_16x16x32_bf16 v[52:55], v[166:169], v[190:193], v[52:55]
	v_mfma_f32_16x16x32_bf16 v[48:51], v[174:177], v[190:193], v[48:51]
	v_mfma_f32_16x16x32_bf16 v[16:19], v[222:225], v[190:193], v[16:19]
	v_mfma_f32_16x16x32_bf16 v[20:23], v[214:217], v[190:193], v[20:23]
	v_mfma_f32_16x16x32_bf16 v[28:31], v[214:217], v[182:185], v[28:31]
	v_mfma_f32_16x16x32_bf16 v[24:27], v[222:225], v[182:185], v[24:27]
	v_mfma_f32_16x16x32_bf16 v[56:59], v[174:177], v[182:185], v[56:59]
	v_mfma_f32_16x16x32_bf16 v[60:63], v[166:169], v[182:185], v[60:63]
	s_barrier
	ds_read_b128 v[142:145], v135 offset:32768
	ds_read_b128 v[166:169], v139 offset:32768
	ds_read_b128 v[170:173], v135 offset:34816
	ds_read_b128 v[174:177], v139 offset:34816
	ds_read_b128 v[178:181], v136 offset:32768
	ds_read_b128 v[182:185], v137 offset:32768
	ds_read_b128 v[186:189], v136 offset:34816
	ds_read_b128 v[190:193], v137 offset:34816
	ds_read_b128 v[194:197], v136 offset:36864
	ds_read_b128 v[198:201], v137 offset:36864
	ds_read_b128 v[202:205], v136 offset:38912
	ds_read_b128 v[206:209], v137 offset:38912
	s_add_u32 s82, s20, 0x40000
	s_addc_u32 s83, s21, 0
	s_add_u32 s92, s20, 0x60000
	s_mov_b32 m0, s31
	s_nop 0
	global_load_lds_dwordx4 v130, s[82:83]
	s_addc_u32 s93, s21, 0
	s_mov_b32 m0, s34
	s_nop 0
	global_load_lds_dwordx4 v130, s[92:93]
	ds_read_b128 v[210:213], v135 offset:49152
	ds_read_b128 v[214:217], v139 offset:49152
	ds_read_b128 v[218:221], v135 offset:51200
	ds_read_b128 v[222:225], v139 offset:51200
	s_waitcnt vmcnt(8) lgkmcnt(0)
	s_barrier
	s_waitcnt lgkmcnt(7)
	v_mfma_f32_16x16x32_bf16 v[124:127], v[142:145], v[178:181], v[124:127]
	v_mfma_f32_16x16x32_bf16 v[120:123], v[170:173], v[178:181], v[120:123]
	s_waitcnt lgkmcnt(5)
	v_mfma_f32_16x16x32_bf16 v[88:91], v[218:221], v[178:181], v[88:91]
	v_mfma_f32_16x16x32_bf16 v[92:95], v[210:213], v[178:181], v[92:95]
	s_waitcnt lgkmcnt(3)
	v_mfma_f32_16x16x32_bf16 v[84:87], v[210:213], v[186:189], v[84:87]
	v_mfma_f32_16x16x32_bf16 v[80:83], v[218:221], v[186:189], v[80:83]
	s_waitcnt lgkmcnt(1)
	v_mfma_f32_16x16x32_bf16 v[112:115], v[170:173], v[186:189], v[112:115]
	v_mfma_f32_16x16x32_bf16 v[116:119], v[142:145], v[186:189], v[116:119]
	v_mfma_f32_16x16x32_bf16 v[108:111], v[142:145], v[194:197], v[108:111]
	v_mfma_f32_16x16x32_bf16 v[104:107], v[170:173], v[194:197], v[104:107]
	v_mfma_f32_16x16x32_bf16 v[72:75], v[218:221], v[194:197], v[72:75]
	v_mfma_f32_16x16x32_bf16 v[76:79], v[210:213], v[194:197], v[76:79]
	v_mfma_f32_16x16x32_bf16 v[68:71], v[210:213], v[202:205], v[68:71]
	v_mfma_f32_16x16x32_bf16 v[64:67], v[218:221], v[202:205], v[64:67]
	s_waitcnt lgkmcnt(0)
	v_mfma_f32_16x16x32_bf16 v[96:99], v[170:173], v[202:205], v[96:99]
	v_mfma_f32_16x16x32_bf16 v[100:103], v[142:145], v[202:205], v[100:103]
	s_waitcnt lgkmcnt(3)
	v_mfma_f32_16x16x32_bf16 v[100:103], v[166:169], v[206:209], v[100:103]
	s_waitcnt lgkmcnt(1)
	v_mfma_f32_16x16x32_bf16 v[96:99], v[174:177], v[206:209], v[96:99]
	v_mfma_f32_16x16x32_bf16 v[64:67], v[222:225], v[206:209], v[64:67]
	v_mfma_f32_16x16x32_bf16 v[68:71], v[214:217], v[206:209], v[68:71]
	v_mfma_f32_16x16x32_bf16 v[76:79], v[214:217], v[198:201], v[76:79]
	v_mfma_f32_16x16x32_bf16 v[72:75], v[222:225], v[198:201], v[72:75]
	v_mfma_f32_16x16x32_bf16 v[104:107], v[174:177], v[198:201], v[104:107]
	v_mfma_f32_16x16x32_bf16 v[108:111], v[166:169], v[198:201], v[108:111]
	v_mfma_f32_16x16x32_bf16 v[116:119], v[166:169], v[190:193], v[116:119]
	s_waitcnt lgkmcnt(0)
	v_mfma_f32_16x16x32_bf16 v[112:115], v[174:177], v[190:193], v[112:115]
	v_mfma_f32_16x16x32_bf16 v[80:83], v[222:225], v[190:193], v[80:83]
	v_mfma_f32_16x16x32_bf16 v[84:87], v[214:217], v[190:193], v[84:87]
	v_mfma_f32_16x16x32_bf16 v[92:95], v[214:217], v[182:185], v[92:95]
	v_mfma_f32_16x16x32_bf16 v[88:91], v[222:225], v[182:185], v[88:91]
	v_mfma_f32_16x16x32_bf16 v[120:123], v[174:177], v[182:185], v[120:123]
	v_mfma_f32_16x16x32_bf16 v[124:127], v[166:169], v[182:185], v[124:127]
	s_barrier
; template <int N, int K, int EPI>
; __device__ void gemm_phase(const u16* __restrict__ A, const u16* __restrict__ Bt, const EpiArgs ea, char* smem, int tid) {
;     ...
;     for (int t = 0; t < nt; t += 2) {
	s_or_b32 s70, s70, 64
	s_add_u32 s82, s18, 0x80
	s_addc_u32 s83, s19, 0
	s_add_u32 s18, s18, 0x20080
	s_mov_b32 m0, s35
	s_nop 0
	global_load_lds_dwordx4 v130, s[82:83]
	s_addc_u32 s19, s19, 0
	s_mov_b32 m0, s36
	s_nop 0
	global_load_lds_dwordx4 v130, s[18:19]
	ds_read_b128 v[178:181], v136 offset:49152
	ds_read_b128 v[182:185], v137 offset:49152
	ds_read_b128 v[186:189], v136 offset:51200
	ds_read_b128 v[190:193], v137 offset:51200
	ds_read_b128 v[194:197], v136 offset:53248
	ds_read_b128 v[198:201], v137 offset:53248
	ds_read_b128 v[202:205], v136 offset:55296
	ds_read_b128 v[206:209], v137 offset:55296
	s_add_u32 s18, s20, 0x80
	s_addc_u32 s19, s21, 0
	s_add_u32 s20, s20, 0x20080
	s_mov_b32 m0, s37
	s_nop 0
	global_load_lds_dwordx4 v130, s[18:19]
	s_addc_u32 s21, s21, 0
	s_mov_b32 m0, s42
	s_nop 0
	global_load_lds_dwordx4 v130, s[20:21]
	s_lshl_b64 s[18:19], s[70:71], 1
	s_add_u32 s18, vcc_hi, s18
	s_addc_u32 s19, vcc_lo, s19
	s_add_u32 s20, s18, 0x20000
	s_mov_b32 m0, s43
	s_nop 0
	global_load_lds_dwordx4 v130, s[18:19]
	s_addc_u32 s21, s19, 0
	s_mov_b32 m0, s66
	s_nop 0
	global_load_lds_dwordx4 v130, s[20:21]
	s_waitcnt vmcnt(8) lgkmcnt(0)
	s_barrier
	s_waitcnt lgkmcnt(7)
	v_mfma_f32_16x16x32_bf16 v[60:63], v[142:145], v[178:181], v[60:63]
	v_mfma_f32_16x16x32_bf16 v[56:59], v[170:173], v[178:181], v[56:59]
	s_waitcnt lgkmcnt(5)
	v_mfma_f32_16x16x32_bf16 v[24:27], v[218:221], v[178:181], v[24:27]
	v_mfma_f32_16x16x32_bf16 v[28:31], v[210:213], v[178:181], v[28:31]
	s_waitcnt lgkmcnt(3)
	v_mfma_f32_16x16x32_bf16 v[20:23], v[210:213], v[186:189], v[20:23]
	v_mfma_f32_16x16x32_bf16 v[16:19], v[218:221], v[186:189], v[16:19]
	s_waitcnt lgkmcnt(1)
	v_mfma_f32_16x16x32_bf16 v[48:51], v[170:173], v[186:189], v[48:51]
	v_mfma_f32_16x16x32_bf16 v[52:55], v[142:145], v[186:189], v[52:55]
	v_mfma_f32_16x16x32_bf16 v[44:47], v[142:145], v[194:197], v[44:47]
	v_mfma_f32_16x16x32_bf16 v[40:43], v[170:173], v[194:197], v[40:43]
	v_mfma_f32_16x16x32_bf16 v[8:11], v[218:221], v[194:197], v[8:11]
	v_mfma_f32_16x16x32_bf16 v[12:15], v[210:213], v[194:197], v[12:15]
	v_mfma_f32_16x16x32_bf16 v[4:7], v[210:213], v[202:205], v[4:7]
	v_mfma_f32_16x16x32_bf16 v[0:3], v[218:221], v[202:205], v[0:3]
	s_waitcnt lgkmcnt(0)
	v_mfma_f32_16x16x32_bf16 v[32:35], v[170:173], v[202:205], v[32:35]
	v_mfma_f32_16x16x32_bf16 v[36:39], v[142:145], v[202:205], v[36:39]
	v_mfma_f32_16x16x32_bf16 v[36:39], v[166:169], v[206:209], v[36:39]
	v_mfma_f32_16x16x32_bf16 v[32:35], v[174:177], v[206:209], v[32:35]
	v_mfma_f32_16x16x32_bf16 v[0:3], v[222:225], v[206:209], v[0:3]
	v_mfma_f32_16x16x32_bf16 v[4:7], v[214:217], v[206:209], v[4:7]
	v_mfma_f32_16x16x32_bf16 v[12:15], v[214:217], v[198:201], v[12:15]
	v_mfma_f32_16x16x32_bf16 v[8:11], v[222:225], v[198:201], v[8:11]
	v_mfma_f32_16x16x32_bf16 v[40:43], v[174:177], v[198:201], v[40:43]
	v_mfma_f32_16x16x32_bf16 v[44:47], v[166:169], v[198:201], v[44:47]
	v_mfma_f32_16x16x32_bf16 v[52:55], v[166:169], v[190:193], v[52:55]
	v_mfma_f32_16x16x32_bf16 v[48:51], v[174:177], v[190:193], v[48:51]
	v_mfma_f32_16x16x32_bf16 v[16:19], v[222:225], v[190:193], v[16:19]
	v_mfma_f32_16x16x32_bf16 v[20:23], v[214:217], v[190:193], v[20:23]
	v_mfma_f32_16x16x32_bf16 v[28:31], v[214:217], v[182:185], v[28:31]
	v_mfma_f32_16x16x32_bf16 v[24:27], v[222:225], v[182:185], v[24:27]
	v_mfma_f32_16x16x32_bf16 v[56:59], v[174:177], v[182:185], v[56:59]
	v_mfma_f32_16x16x32_bf16 v[60:63], v[166:169], v[182:185], v[60:63]
	s_add_i32 s3, s3, 2
	s_addk_i32 s5, 0x80
	s_add_u32 s16, s16, 0x100
	s_addc_u32 s17, s17, 0
	s_cmp_gt_u32 s3, 13
	s_barrier
	s_cbranch_scc0 .LBB0_64
; #define WAIT_V(n) asm volatile("s_waitcnt vmcnt(" #n ")" ::: "memory")
; #define BAR __builtin_amdgcn_s_barrier()
; template <int N, int K, int EPI>
; __device__ void gemm_phase(const u16* __restrict__ A, const u16* __restrict__ Bt, const EpiArgs ea, char* smem, int tid) {
;     ...
;       } else if constexpr (EPI == EPI_F) {
;         u16* f = ea.o0;
; #pragma unroll
;         for (int ai = 0; ai < 2; ++ai)
; #pragma unroll
;           for (int bj = 0; bj < 2; ++bj)
; #pragma unroll
;             for (int m = 0; m < 4; ++m) {
;               const int row = brow + ai * HALF + wr * 64 + m * 16 + fr_e;
;               const int col = pn * BM + bj * HALF + wc * 32 + fq_e * 8;
;               const f32x4 v0 = acc[ai][bj][m][0], v1 = acc[ai][bj][m][1];
;               u32x4 o = {pk_bf16(v0[0], v0[1]), pk_bf16(v0[2], v0[3]), pk_bf16(v1[0], v1[1]), pk_bf16(v1[2], v1[3])};
;               *(u32x4*)(f + (size_t)row * N + col) = o;
;             }
;     ...
;     if (!has_next) break;
; #pragma unroll
;     for (int ai = 0; ai < 2; ++ai)
; #pragma unroll
;       for (int bj = 0; bj < 2; ++bj)
; #pragma unroll
;         for (int m = 0; m < 4; ++m)
; #pragma unroll
;           for (int n = 0; n < 2; ++n) acc[ai][bj][m][n] = f32x4{0.f, 0.f, 0.f, 0.f};
;     v = vn; pm = pmn; pn = pnn; Ab = Abn; Bb = Bbn;
;   }
;   WAIT_V(0);
;   if (wr == 0) BAR;
	s_lshl_b32 s3, s24, 8
	v_mov_b32_e32 v128, v131
	v_mov_b32_e32 v129, v132
	s_add_i32 s3, s3, s67
	v_cvt_pk_bf16_f32 v124, v124, v125
	v_cvt_pk_bf16_f32 v125, v126, v127
	v_cvt_pk_bf16_f32 v126, v120, v121
	v_cvt_pk_bf16_f32 v127, v122, v123
	v_cvt_pk_bf16_f32 v116, v116, v117
	s_nop 0
	v_add_u32_e32 v142, s3, v128
	s_lshl_b32 s3, s95, 8
	s_or_b32 s3, s3, s88
	v_lshl_add_u32 v144, v129, 3, s3
	v_ashrrev_i32_e32 v145, 31, v144
	v_ashrrev_i32_e32 v143, 31, v142
	v_lshl_add_u64 v[128:129], v[144:145], 1, s[64:65]
	v_lshlrev_b64 v[120:121], 11, v[142:143]
	v_lshl_add_u64 v[122:123], v[128:129], 0, v[120:121]
	global_store_dwordx4 v[122:123], v[124:127], off
	v_add_u32_e32 v122, 16, v142
	v_ashrrev_i32_e32 v123, 31, v122
	v_cvt_pk_bf16_f32 v117, v118, v119
	v_cvt_pk_bf16_f32 v118, v112, v113
	v_lshlrev_b64 v[112:113], 11, v[122:123]
	v_cvt_pk_bf16_f32 v119, v114, v115
	v_lshl_add_u64 v[114:115], v[128:129], 0, v[112:113]
	global_store_dwordx4 v[114:115], v[116:119], off
	v_add_u32_e32 v114, 32, v142
	v_ashrrev_i32_e32 v115, 31, v114
	v_cvt_pk_bf16_f32 v108, v108, v109
	v_cvt_pk_bf16_f32 v109, v110, v111
	v_cvt_pk_bf16_f32 v110, v104, v105
	v_lshlrev_b64 v[104:105], 11, v[114:115]
	v_cvt_pk_bf16_f32 v111, v106, v107
	v_lshl_add_u64 v[106:107], v[128:129], 0, v[104:105]
	global_store_dwordx4 v[106:107], v[108:111], off
	v_add_u32_e32 v106, 48, v142
	v_ashrrev_i32_e32 v107, 31, v106
	v_cvt_pk_bf16_f32 v100, v100, v101
	v_cvt_pk_bf16_f32 v101, v102, v103
	v_cvt_pk_bf16_f32 v102, v96, v97
	v_lshlrev_b64 v[96:97], 11, v[106:107]
	v_cvt_pk_bf16_f32 v103, v98, v99
	v_lshl_add_u64 v[98:99], v[128:129], 0, v[96:97]
	global_store_dwordx4 v[98:99], v[100:103], off
	v_add_u32_e32 v98, 0x80, v144
	v_ashrrev_i32_e32 v99, 31, v98
	v_lshl_add_u64 v[98:99], v[98:99], 1, s[64:65]
	v_cvt_pk_bf16_f32 v68, v68, v69
	v_cvt_pk_bf16_f32 v69, v70, v71
	v_cvt_pk_bf16_f32 v70, v64, v65
	v_lshl_add_u64 v[64:65], v[98:99], 0, v[96:97]
	v_cvt_pk_bf16_f32 v71, v66, v67
	global_store_dwordx4 v[64:65], v[68:71], off
	v_add_u32_e32 v64, 0x80, v142
	v_ashrrev_i32_e32 v65, 31, v64
	v_cvt_pk_bf16_f32 v60, v60, v61
	v_cvt_pk_bf16_f32 v61, v62, v63
	v_cvt_pk_bf16_f32 v62, v56, v57
	v_lshlrev_b64 v[56:57], 11, v[64:65]
	v_cvt_pk_bf16_f32 v92, v92, v93
	v_cvt_pk_bf16_f32 v93, v94, v95
	v_cvt_pk_bf16_f32 v94, v88, v89
	v_lshl_add_u64 v[88:89], v[98:99], 0, v[120:121]
	v_cvt_pk_bf16_f32 v84, v84, v85
	v_cvt_pk_bf16_f32 v85, v86, v87
	v_cvt_pk_bf16_f32 v86, v80, v81
	v_lshl_add_u64 v[80:81], v[98:99], 0, v[112:113]
	v_cvt_pk_bf16_f32 v76, v76, v77
	v_cvt_pk_bf16_f32 v77, v78, v79
	v_cvt_pk_bf16_f32 v78, v72, v73
	v_lshl_add_u64 v[72:73], v[98:99], 0, v[104:105]
	v_cvt_pk_bf16_f32 v63, v58, v59
	v_lshl_add_u64 v[58:59], v[128:129], 0, v[56:57]
	v_cvt_pk_bf16_f32 v95, v90, v91
	global_store_dwordx4 v[88:89], v[92:95], off
	v_cvt_pk_bf16_f32 v87, v82, v83
	global_store_dwordx4 v[80:81], v[84:87], off
	v_cvt_pk_bf16_f32 v79, v74, v75
	global_store_dwordx4 v[72:73], v[76:79], off
	global_store_dwordx4 v[58:59], v[60:63], off
	v_add_u32_e32 v58, 0x90, v142
	v_ashrrev_i32_e32 v59, 31, v58
	v_cvt_pk_bf16_f32 v52, v52, v53
	v_cvt_pk_bf16_f32 v53, v54, v55
	v_cvt_pk_bf16_f32 v54, v48, v49
	v_lshlrev_b64 v[48:49], 11, v[58:59]
	v_cvt_pk_bf16_f32 v55, v50, v51
	v_lshl_add_u64 v[50:51], v[128:129], 0, v[48:49]
	global_store_dwordx4 v[50:51], v[52:55], off
	v_add_u32_e32 v50, 0xa0, v142
	v_ashrrev_i32_e32 v51, 31, v50
	v_cvt_pk_bf16_f32 v44, v44, v45
	v_cvt_pk_bf16_f32 v45, v46, v47
	v_cvt_pk_bf16_f32 v46, v40, v41
	v_lshlrev_b64 v[40:41], 11, v[50:51]
	v_cvt_pk_bf16_f32 v47, v42, v43
	v_lshl_add_u64 v[42:43], v[128:129], 0, v[40:41]
	global_store_dwordx4 v[42:43], v[44:47], off
	v_add_u32_e32 v42, 0xb0, v142
	v_ashrrev_i32_e32 v43, 31, v42
	v_cvt_pk_bf16_f32 v36, v36, v37
	v_cvt_pk_bf16_f32 v37, v38, v39
	v_cvt_pk_bf16_f32 v38, v32, v33
	v_lshlrev_b64 v[32:33], 11, v[42:43]
	v_cvt_pk_bf16_f32 v39, v34, v35
	v_lshl_add_u64 v[34:35], v[128:129], 0, v[32:33]
	v_cvt_pk_bf16_f32 v28, v28, v29
	v_cvt_pk_bf16_f32 v29, v30, v31
	v_cvt_pk_bf16_f32 v30, v24, v25
	v_lshl_add_u64 v[24:25], v[98:99], 0, v[56:57]
	v_cvt_pk_bf16_f32 v20, v20, v21
	v_cvt_pk_bf16_f32 v21, v22, v23
	v_cvt_pk_bf16_f32 v22, v16, v17
	v_lshl_add_u64 v[16:17], v[98:99], 0, v[48:49]
	v_cvt_pk_bf16_f32 v12, v12, v13
	v_cvt_pk_bf16_f32 v13, v14, v15
	v_cvt_pk_bf16_f32 v14, v8, v9
	v_lshl_add_u64 v[8:9], v[98:99], 0, v[40:41]
	v_cvt_pk_bf16_f32 v4, v4, v5
	v_cvt_pk_bf16_f32 v5, v6, v7
	v_cvt_pk_bf16_f32 v6, v0, v1
	v_lshl_add_u64 v[0:1], v[98:99], 0, v[32:33]
	s_and_b64 vcc, exec, s[0:1]
	s_mov_b32 s24, s2
	s_mov_b32 s95, s4
	s_mov_b64 s[14:15], s[10:11]
	s_mov_b64 s[12:13], s[8:9]
	global_store_dwordx4 v[34:35], v[36:39], off
	v_cvt_pk_bf16_f32 v31, v26, v27
	global_store_dwordx4 v[24:25], v[28:31], off
	v_cvt_pk_bf16_f32 v23, v18, v19
	global_store_dwordx4 v[16:17], v[20:23], off
	v_cvt_pk_bf16_f32 v15, v10, v11
	global_store_dwordx4 v[8:9], v[12:15], off
	v_cvt_pk_bf16_f32 v7, v2, v3
	global_store_dwordx4 v[0:1], v[4:7], off
	s_cbranch_vccz .LBB0_61
	s_setprio 0
	s_waitcnt vmcnt(0)
	v_readlane_b32 s0, v226, 16
	v_readlane_b32 s36, v226, 30
	v_readlane_b32 s18, v226, 22
	v_readlane_b32 s92, v226, 20
	s_cmpk_gt_u32 s0, 0xff
	v_readlane_b32 s37, v226, 31
	v_readlane_b32 s31, v226, 34
	v_readlane_b32 s42, v226, 29
	v_readlane_b32 s43, v226, 28
	v_readlane_b32 s66, v226, 27
	v_readlane_b32 s67, v226, 26
	v_readlane_b32 s19, v226, 23
	v_readlane_b32 s93, v226, 21
	s_cbranch_scc1 .LBB0_68
	s_barrier

; template <int N, int K, int EPI>
; __device__ void gemm_phase(const u16* __restrict__ A, const u16* __restrict__ Bt, const EpiArgs ea, char* smem, int tid) {
;     ...
;     for (int t = 0; t < nt; t += 2) {
;       const bool lastit = (t == nt - 2);
;       const u16* A2 = lastit ? Abn : Ab;
;       const u16* B2 = lastit ? Bbn : Bb;
;       const int k2 = lastit ? 0 : t + 2;
;       BODY(Ab, t + 1, A2, B2, k2, k2 + 1);
.LBB0_110:
	ds_read_b128 v[128:131], v169
	ds_read_b128 v[134:137], v173
	ds_read_b128 v[138:141], v169 offset:2048
	ds_read_b128 v[142:145], v173 offset:2048
	s_add_u32 s16, s14, 0x40080
	s_addc_u32 s17, s15, 0
	s_add_u32 s18, s14, 0x60080
	s_addc_u32 s19, s15, 0
	s_cmp_eq_u32 s3, 12
	s_cselect_b32 s82, s11, s13
	s_cselect_b32 s83, s10, s12
	s_cselect_b32 s88, s9, s5
	s_cselect_b32 s89, s8, s4
	s_nop 0
	ds_read_b128 v[176:179], v170
	ds_read_b128 v[180:183], v171
	ds_read_b128 v[184:187], v170 offset:2048
	ds_read_b128 v[188:191], v171 offset:2048
	ds_read_b128 v[192:195], v170 offset:4096
	ds_read_b128 v[196:199], v171 offset:4096
	ds_read_b128 v[200:203], v170 offset:6144
	ds_read_b128 v[204:207], v171 offset:6144
	s_mov_b32 m0, s66
	s_nop 0
	global_load_lds_dwordx4 v165, s[16:17]
	s_nop 0
	s_mov_b32 m0, s67
	s_nop 0
	global_load_lds_dwordx4 v165, s[18:19]
	ds_read_b128 v[208:211], v169 offset:16384
	ds_read_b128 v[212:215], v173 offset:16384
	ds_read_b128 v[216:219], v169 offset:18432
	ds_read_b128 v[220:223], v173 offset:18432
	s_waitcnt vmcnt(8) lgkmcnt(0)
	s_barrier
	s_waitcnt lgkmcnt(7)
	v_mfma_f32_16x16x32_bf16 v[124:127], v[128:131], v[176:179], v[124:127]
	v_mfma_f32_16x16x32_bf16 v[120:123], v[138:141], v[176:179], v[120:123]
	s_waitcnt lgkmcnt(5)
	v_mfma_f32_16x16x32_bf16 v[88:91], v[216:219], v[176:179], v[88:91]
	v_mfma_f32_16x16x32_bf16 v[92:95], v[208:211], v[176:179], v[92:95]
	s_waitcnt lgkmcnt(3)
	v_mfma_f32_16x16x32_bf16 v[84:87], v[208:211], v[184:187], v[84:87]
	v_mfma_f32_16x16x32_bf16 v[80:83], v[216:219], v[184:187], v[80:83]
	s_waitcnt lgkmcnt(1)
	v_mfma_f32_16x16x32_bf16 v[112:115], v[138:141], v[184:187], v[112:115]
	v_mfma_f32_16x16x32_bf16 v[116:119], v[128:131], v[184:187], v[116:119]
	v_mfma_f32_16x16x32_bf16 v[108:111], v[128:131], v[192:195], v[108:111]
	v_mfma_f32_16x16x32_bf16 v[104:107], v[138:141], v[192:195], v[104:107]
	v_mfma_f32_16x16x32_bf16 v[72:75], v[216:219], v[192:195], v[72:75]
	v_mfma_f32_16x16x32_bf16 v[76:79], v[208:211], v[192:195], v[76:79]
	v_mfma_f32_16x16x32_bf16 v[68:71], v[208:211], v[200:203], v[68:71]
	v_mfma_f32_16x16x32_bf16 v[64:67], v[216:219], v[200:203], v[64:67]
	s_waitcnt lgkmcnt(0)
	v_mfma_f32_16x16x32_bf16 v[96:99], v[138:141], v[200:203], v[96:99]
	v_mfma_f32_16x16x32_bf16 v[100:103], v[128:131], v[200:203], v[100:103]
	s_waitcnt lgkmcnt(3)
	v_mfma_f32_16x16x32_bf16 v[100:103], v[134:137], v[204:207], v[100:103]
	s_waitcnt lgkmcnt(1)
	v_mfma_f32_16x16x32_bf16 v[96:99], v[142:145], v[204:207], v[96:99]
	v_mfma_f32_16x16x32_bf16 v[64:67], v[220:223], v[204:207], v[64:67]
	v_mfma_f32_16x16x32_bf16 v[68:71], v[212:215], v[204:207], v[68:71]
	v_mfma_f32_16x16x32_bf16 v[76:79], v[212:215], v[196:199], v[76:79]
	v_mfma_f32_16x16x32_bf16 v[72:75], v[220:223], v[196:199], v[72:75]
	v_mfma_f32_16x16x32_bf16 v[104:107], v[142:145], v[196:199], v[104:107]
	v_mfma_f32_16x16x32_bf16 v[108:111], v[134:137], v[196:199], v[108:111]
	v_mfma_f32_16x16x32_bf16 v[116:119], v[134:137], v[188:191], v[116:119]
	s_waitcnt lgkmcnt(0)
	v_mfma_f32_16x16x32_bf16 v[112:115], v[142:145], v[188:191], v[112:115]
	v_mfma_f32_16x16x32_bf16 v[80:83], v[220:223], v[188:191], v[80:83]
	v_mfma_f32_16x16x32_bf16 v[84:87], v[212:215], v[188:191], v[84:87]
	v_mfma_f32_16x16x32_bf16 v[92:95], v[212:215], v[180:183], v[92:95]
	v_mfma_f32_16x16x32_bf16 v[88:91], v[220:223], v[180:183], v[88:91]
	v_mfma_f32_16x16x32_bf16 v[120:123], v[142:145], v[180:183], v[120:123]
	v_mfma_f32_16x16x32_bf16 v[124:127], v[134:137], v[180:183], v[124:127]
	s_barrier
	s_cselect_b32 s70, 0, s7
	s_lshl_b64 s[92:93], s[70:71], 1
	s_add_u32 s16, s83, s92
	s_addc_u32 s17, s82, s93
	s_add_u32 s18, s16, 0x20000
	s_mov_b32 m0, s24
	s_nop 0
	global_load_lds_dwordx4 v165, s[16:17]
	s_addc_u32 s19, s17, 0
	s_mov_b32 m0, s25
	s_nop 0
	global_load_lds_dwordx4 v165, s[18:19]
	ds_read_b128 v[176:179], v170 offset:16384
	ds_read_b128 v[180:183], v171 offset:16384
	ds_read_b128 v[184:187], v170 offset:18432
	ds_read_b128 v[188:191], v171 offset:18432
	ds_read_b128 v[192:195], v170 offset:20480
	ds_read_b128 v[196:199], v171 offset:20480
	ds_read_b128 v[200:203], v170 offset:22528
	ds_read_b128 v[204:207], v171 offset:22528
	s_add_u32 s18, s89, s92
	s_addc_u32 s19, s88, s93
	s_add_u32 s88, s18, 0x20000
	s_mov_b32 m0, s23
	s_nop 0
	global_load_lds_dwordx4 v165, s[18:19]
	s_addc_u32 s89, s19, 0
	s_mov_b32 m0, s26
	s_nop 0
	global_load_lds_dwordx4 v165, s[88:89]
	s_add_u32 s83, s83, 0x40000
	s_addc_u32 s82, s82, 0
	s_add_u32 s88, s83, s92
	s_addc_u32 s89, s82, s93
	s_add_u32 s92, s88, 0x20000
	s_mov_b32 m0, s27
	s_nop 0
	global_load_lds_dwordx4 v165, s[88:89]
	s_addc_u32 s93, s89, 0
	s_mov_b32 m0, s28
	s_nop 0
	global_load_lds_dwordx4 v165, s[92:93]
	s_waitcnt vmcnt(8) lgkmcnt(0)
	s_barrier
	s_waitcnt lgkmcnt(7)
	v_mfma_f32_16x16x32_bf16 v[60:63], v[128:131], v[176:179], v[60:63]
	v_mfma_f32_16x16x32_bf16 v[56:59], v[138:141], v[176:179], v[56:59]
	s_waitcnt lgkmcnt(5)
	v_mfma_f32_16x16x32_bf16 v[24:27], v[216:219], v[176:179], v[24:27]
	v_mfma_f32_16x16x32_bf16 v[28:31], v[208:211], v[176:179], v[28:31]
	s_waitcnt lgkmcnt(3)
	v_mfma_f32_16x16x32_bf16 v[20:23], v[208:211], v[184:187], v[20:23]
	v_mfma_f32_16x16x32_bf16 v[16:19], v[216:219], v[184:187], v[16:19]
	s_waitcnt lgkmcnt(1)
	v_mfma_f32_16x16x32_bf16 v[48:51], v[138:141], v[184:187], v[48:51]
	v_mfma_f32_16x16x32_bf16 v[52:55], v[128:131], v[184:187], v[52:55]
	v_mfma_f32_16x16x32_bf16 v[44:47], v[128:131], v[192:195], v[44:47]
	v_mfma_f32_16x16x32_bf16 v[40:43], v[138:141], v[192:195], v[40:43]
	v_mfma_f32_16x16x32_bf16 v[8:11], v[216:219], v[192:195], v[8:11]
	v_mfma_f32_16x16x32_bf16 v[12:15], v[208:211], v[192:195], v[12:15]
	v_mfma_f32_16x16x32_bf16 v[4:7], v[208:211], v[200:203], v[4:7]
	v_mfma_f32_16x16x32_bf16 v[0:3], v[216:219], v[200:203], v[0:3]
	s_waitcnt lgkmcnt(0)
	v_mfma_f32_16x16x32_bf16 v[32:35], v[138:141], v[200:203], v[32:35]
	v_mfma_f32_16x16x32_bf16 v[36:39], v[128:131], v[200:203], v[36:39]
	v_mfma_f32_16x16x32_bf16 v[36:39], v[134:137], v[204:207], v[36:39]
	v_mfma_f32_16x16x32_bf16 v[32:35], v[142:145], v[204:207], v[32:35]
	v_mfma_f32_16x16x32_bf16 v[0:3], v[220:223], v[204:207], v[0:3]
	v_mfma_f32_16x16x32_bf16 v[4:7], v[212:215], v[204:207], v[4:7]
	v_mfma_f32_16x16x32_bf16 v[12:15], v[212:215], v[196:199], v[12:15]
	v_mfma_f32_16x16x32_bf16 v[8:11], v[220:223], v[196:199], v[8:11]
	v_mfma_f32_16x16x32_bf16 v[40:43], v[142:145], v[196:199], v[40:43]
	v_mfma_f32_16x16x32_bf16 v[44:47], v[134:137], v[196:199], v[44:47]
	v_mfma_f32_16x16x32_bf16 v[52:55], v[134:137], v[188:191], v[52:55]
	v_mfma_f32_16x16x32_bf16 v[48:51], v[142:145], v[188:191], v[48:51]
	v_mfma_f32_16x16x32_bf16 v[16:19], v[220:223], v[188:191], v[16:19]
	v_mfma_f32_16x16x32_bf16 v[20:23], v[212:215], v[188:191], v[20:23]
	v_mfma_f32_16x16x32_bf16 v[28:31], v[212:215], v[180:183], v[28:31]
	v_mfma_f32_16x16x32_bf16 v[24:27], v[220:223], v[180:183], v[24:27]
	v_mfma_f32_16x16x32_bf16 v[56:59], v[142:145], v[180:183], v[56:59]
	v_mfma_f32_16x16x32_bf16 v[60:63], v[134:137], v[180:183], v[60:63]
	s_barrier
	ds_read_b128 v[128:131], v169 offset:32768
	ds_read_b128 v[134:137], v173 offset:32768
	ds_read_b128 v[138:141], v169 offset:34816
	ds_read_b128 v[142:145], v173 offset:34816
	ds_read_b128 v[176:179], v170 offset:32768
	ds_read_b128 v[180:183], v171 offset:32768
	ds_read_b128 v[184:187], v170 offset:34816
	ds_read_b128 v[188:191], v171 offset:34816
	ds_read_b128 v[192:195], v170 offset:36864
	ds_read_b128 v[196:199], v171 offset:36864
	ds_read_b128 v[200:203], v170 offset:38912
	ds_read_b128 v[204:207], v171 offset:38912
	s_add_u32 s88, s18, 0x40000
	s_addc_u32 s89, s19, 0
	s_add_u32 s92, s18, 0x60000
	s_mov_b32 m0, s29
	s_nop 0
	global_load_lds_dwordx4 v165, s[88:89]
	s_addc_u32 s93, s19, 0
	s_mov_b32 m0, s30
	s_nop 0
	global_load_lds_dwordx4 v165, s[92:93]
	ds_read_b128 v[208:211], v169 offset:49152
	ds_read_b128 v[212:215], v173 offset:49152
	ds_read_b128 v[216:219], v169 offset:51200
	ds_read_b128 v[220:223], v173 offset:51200
	s_waitcnt vmcnt(8) lgkmcnt(0)
	s_barrier
	s_waitcnt lgkmcnt(7)
	v_mfma_f32_16x16x32_bf16 v[124:127], v[128:131], v[176:179], v[124:127]
	v_mfma_f32_16x16x32_bf16 v[120:123], v[138:141], v[176:179], v[120:123]
	s_waitcnt lgkmcnt(5)
	v_mfma_f32_16x16x32_bf16 v[88:91], v[216:219], v[176:179], v[88:91]
	v_mfma_f32_16x16x32_bf16 v[92:95], v[208:211], v[176:179], v[92:95]
	s_waitcnt lgkmcnt(3)
	v_mfma_f32_16x16x32_bf16 v[84:87], v[208:211], v[184:187], v[84:87]
	v_mfma_f32_16x16x32_bf16 v[80:83], v[216:219], v[184:187], v[80:83]
	s_waitcnt lgkmcnt(1)
	v_mfma_f32_16x16x32_bf16 v[112:115], v[138:141], v[184:187], v[112:115]
	v_mfma_f32_16x16x32_bf16 v[116:119], v[128:131], v[184:187], v[116:119]
	v_mfma_f32_16x16x32_bf16 v[108:111], v[128:131], v[192:195], v[108:111]
	v_mfma_f32_16x16x32_bf16 v[104:107], v[138:141], v[192:195], v[104:107]
	v_mfma_f32_16x16x32_bf16 v[72:75], v[216:219], v[192:195], v[72:75]
	v_mfma_f32_16x16x32_bf16 v[76:79], v[208:211], v[192:195], v[76:79]
	v_mfma_f32_16x16x32_bf16 v[68:71], v[208:211], v[200:203], v[68:71]
	v_mfma_f32_16x16x32_bf16 v[64:67], v[216:219], v[200:203], v[64:67]
	s_waitcnt lgkmcnt(0)
	v_mfma_f32_16x16x32_bf16 v[96:99], v[138:141], v[200:203], v[96:99]
	v_mfma_f32_16x16x32_bf16 v[100:103], v[128:131], v[200:203], v[100:103]
	s_waitcnt lgkmcnt(3)
	v_mfma_f32_16x16x32_bf16 v[100:103], v[134:137], v[204:207], v[100:103]
	s_waitcnt lgkmcnt(1)
	v_mfma_f32_16x16x32_bf16 v[96:99], v[142:145], v[204:207], v[96:99]
	v_mfma_f32_16x16x32_bf16 v[64:67], v[220:223], v[204:207], v[64:67]
	v_mfma_f32_16x16x32_bf16 v[68:71], v[212:215], v[204:207], v[68:71]
	v_mfma_f32_16x16x32_bf16 v[76:79], v[212:215], v[196:199], v[76:79]
	v_mfma_f32_16x16x32_bf16 v[72:75], v[220:223], v[196:199], v[72:75]
	v_mfma_f32_16x16x32_bf16 v[104:107], v[142:145], v[196:199], v[104:107]
	v_mfma_f32_16x16x32_bf16 v[108:111], v[134:137], v[196:199], v[108:111]
	v_mfma_f32_16x16x32_bf16 v[116:119], v[134:137], v[188:191], v[116:119]
	s_waitcnt lgkmcnt(0)
	v_mfma_f32_16x16x32_bf16 v[112:115], v[142:145], v[188:191], v[112:115]
	v_mfma_f32_16x16x32_bf16 v[80:83], v[220:223], v[188:191], v[80:83]
	v_mfma_f32_16x16x32_bf16 v[84:87], v[212:215], v[188:191], v[84:87]
	v_mfma_f32_16x16x32_bf16 v[92:95], v[212:215], v[180:183], v[92:95]
	v_mfma_f32_16x16x32_bf16 v[88:91], v[220:223], v[180:183], v[88:91]
	v_mfma_f32_16x16x32_bf16 v[120:123], v[142:145], v[180:183], v[120:123]
	v_mfma_f32_16x16x32_bf16 v[124:127], v[134:137], v[180:183], v[124:127]
	s_barrier
; template <int N, int K, int EPI>
; __device__ void gemm_phase(const u16* __restrict__ A, const u16* __restrict__ Bt, const EpiArgs ea, char* smem, int tid) {
;     ...
;         if (pn == 4 || pn == 5) {
;           u16* vt = ea.o2;
; #pragma unroll
;           for (int ai = 0; ai < 2; ++ai)
; #pragma unroll
;             for (int bj = 0; bj < 2; ++bj)
; #pragma unroll
;               for (int m = 0; m < 4; ++m)
; #pragma unroll
;                 for (int n = 0; n < 2; ++n) {
;                   f32x4 vv = acc[ai][bj][m][n];
;                   const bool b0 = fr_e & 1, b1 = fr_e & 2;
;                   { float sA = b0 ? vv[0] : vv[1], sB = b0 ? vv[2] : vv[3];
;                     float rA = __shfl_xor(sA, 1), rB = __shfl_xor(sB, 1);
;                     if (b0) { vv[0] = rA; vv[2] = rB; } else { vv[1] = rA; vv[3] = rB; } }
;                   { float sC = b1 ? vv[0] : vv[2], sD = b1 ? vv[1] : vv[3];
;                     float rC = __shfl_xor(sC, 2), rD = __shfl_xor(sD, 2);
;                     if (b1) { vv[0] = rC; vv[1] = rD; } else { vv[2] = rC; vv[3] = rD; } }
;                   int row = brow + ai * HALF + wr * 64 + m * 16 + (fr_e & ~3);
;                   int col = (pn - 4) * 256 + bj * HALF + wc * 32 + fq_e * 8 + n * 4 + (fr_e & 3);
;                   int b = row >> 12, sq = row & 4095, hh = col >> 6, dh = col & 63;
;                   u32x2 o = {pk_bf16(vv[0], vv[1]), pk_bf16(vv[2], vv[3])};
;                   *(u32x2*)(vt + ((size_t)(b * 8 + hh) * 64 + dh) * SEQ + sq) = o;
;                 }
;         } else {
;           u16* base; float sc = 1.f; int cbase; bool headed;
;           if (pn < 2) { base = ea.o0; sc = QSCALE; cbase = pn * 256; headed = true; }
;           else if (pn < 4) { base = ea.o1; cbase = (pn - 2) * 256; headed = true; }
;           else { base = ea.o3; cbase = (pn - 6) * 256; headed = false; }
	s_or_b32 s70, s70, 64
	s_add_u32 s88, s16, 0x80
	s_addc_u32 s89, s17, 0
	s_add_u32 s16, s16, 0x20080
	s_mov_b32 m0, s31
	s_nop 0
	global_load_lds_dwordx4 v165, s[88:89]
	s_addc_u32 s17, s17, 0
	s_mov_b32 m0, s34
	s_nop 0
	global_load_lds_dwordx4 v165, s[16:17]
	ds_read_b128 v[176:179], v170 offset:49152
	ds_read_b128 v[180:183], v171 offset:49152
	ds_read_b128 v[184:187], v170 offset:51200
	ds_read_b128 v[188:191], v171 offset:51200
	ds_read_b128 v[192:195], v170 offset:53248
	ds_read_b128 v[196:199], v171 offset:53248
	ds_read_b128 v[200:203], v170 offset:55296
	ds_read_b128 v[204:207], v171 offset:55296
	s_add_u32 s16, s18, 0x80
	s_addc_u32 s17, s19, 0
	s_add_u32 s18, s18, 0x20080
	s_mov_b32 m0, s35
	s_nop 0
	global_load_lds_dwordx4 v165, s[16:17]
	s_addc_u32 s19, s19, 0
	s_mov_b32 m0, s36
	s_nop 0
	global_load_lds_dwordx4 v165, s[18:19]
	s_lshl_b64 s[16:17], s[70:71], 1
	s_add_u32 s16, s83, s16
	s_addc_u32 s17, s82, s17
	s_add_u32 s18, s16, 0x20000
	s_mov_b32 m0, s37
	s_nop 0
	global_load_lds_dwordx4 v165, s[16:17]
	s_addc_u32 s19, s17, 0
	s_mov_b32 m0, s42
	s_nop 0
	global_load_lds_dwordx4 v165, s[18:19]
	s_waitcnt vmcnt(8) lgkmcnt(0)
	s_barrier
	s_waitcnt lgkmcnt(7)
	v_mfma_f32_16x16x32_bf16 v[60:63], v[128:131], v[176:179], v[60:63]
	v_mfma_f32_16x16x32_bf16 v[56:59], v[138:141], v[176:179], v[56:59]
	s_waitcnt lgkmcnt(5)
	v_mfma_f32_16x16x32_bf16 v[24:27], v[216:219], v[176:179], v[24:27]
	v_mfma_f32_16x16x32_bf16 v[28:31], v[208:211], v[176:179], v[28:31]
	s_waitcnt lgkmcnt(3)
	v_mfma_f32_16x16x32_bf16 v[20:23], v[208:211], v[184:187], v[20:23]
	v_mfma_f32_16x16x32_bf16 v[16:19], v[216:219], v[184:187], v[16:19]
	s_waitcnt lgkmcnt(1)
	v_mfma_f32_16x16x32_bf16 v[48:51], v[138:141], v[184:187], v[48:51]
	v_mfma_f32_16x16x32_bf16 v[52:55], v[128:131], v[184:187], v[52:55]
	v_mfma_f32_16x16x32_bf16 v[44:47], v[128:131], v[192:195], v[44:47]
	v_mfma_f32_16x16x32_bf16 v[40:43], v[138:141], v[192:195], v[40:43]
	v_mfma_f32_16x16x32_bf16 v[8:11], v[216:219], v[192:195], v[8:11]
	v_mfma_f32_16x16x32_bf16 v[12:15], v[208:211], v[192:195], v[12:15]
	v_mfma_f32_16x16x32_bf16 v[4:7], v[208:211], v[200:203], v[4:7]
	v_mfma_f32_16x16x32_bf16 v[0:3], v[216:219], v[200:203], v[0:3]
	s_waitcnt lgkmcnt(0)
	v_mfma_f32_16x16x32_bf16 v[32:35], v[138:141], v[200:203], v[32:35]
	v_mfma_f32_16x16x32_bf16 v[36:39], v[128:131], v[200:203], v[36:39]
	v_mfma_f32_16x16x32_bf16 v[36:39], v[134:137], v[204:207], v[36:39]
	v_mfma_f32_16x16x32_bf16 v[32:35], v[142:145], v[204:207], v[32:35]
	v_mfma_f32_16x16x32_bf16 v[0:3], v[220:223], v[204:207], v[0:3]
	v_mfma_f32_16x16x32_bf16 v[4:7], v[212:215], v[204:207], v[4:7]
	v_mfma_f32_16x16x32_bf16 v[12:15], v[212:215], v[196:199], v[12:15]
	v_mfma_f32_16x16x32_bf16 v[8:11], v[220:223], v[196:199], v[8:11]
	v_mfma_f32_16x16x32_bf16 v[40:43], v[142:145], v[196:199], v[40:43]
	v_mfma_f32_16x16x32_bf16 v[44:47], v[134:137], v[196:199], v[44:47]
	v_mfma_f32_16x16x32_bf16 v[52:55], v[134:137], v[188:191], v[52:55]
	v_mfma_f32_16x16x32_bf16 v[48:51], v[142:145], v[188:191], v[48:51]
	v_mfma_f32_16x16x32_bf16 v[16:19], v[220:223], v[188:191], v[16:19]
	v_mfma_f32_16x16x32_bf16 v[20:23], v[212:215], v[188:191], v[20:23]
	v_mfma_f32_16x16x32_bf16 v[28:31], v[212:215], v[180:183], v[28:31]
	v_mfma_f32_16x16x32_bf16 v[24:27], v[220:223], v[180:183], v[24:27]
	v_mfma_f32_16x16x32_bf16 v[56:59], v[142:145], v[180:183], v[56:59]
	v_mfma_f32_16x16x32_bf16 v[60:63], v[134:137], v[180:183], v[60:63]
	s_add_i32 s3, s3, 2
	s_addk_i32 s7, 0x80
	s_add_u32 s14, s14, 0x100
	s_addc_u32 s15, s15, 0
	s_cmp_gt_u32 s3, 13
	s_barrier
	s_cbranch_scc0 .LBB0_110
	s_lshl_b32 s3, s97, 8
	s_and_b32 s4, s96, -2
	v_mov_b32_e32 v176, v167
	v_mov_b32_e32 v132, v166
	s_cmp_lg_u32 s4, 4
	s_mov_b64 s[4:5], -1
	s_mov_b32 s19, 0x3ffc0
	s_cbranch_scc0 .LBB0_184
	s_cmp_gt_i32 s96, 1
	s_mov_b64 s[14:15], -1
	s_cbranch_scc0 .LBB0_117
	s_lshl_b32 s7, s96, 8
	s_cmp_gt_u32 s96, 3
	s_mov_b64 s[4:5], -1
	s_cbranch_scc0 .LBB0_115
	s_add_i32 s18, s7, 0xfffffa00
	s_mov_b64 s[4:5], 0

; template <int N, int K, int EPI>
; __device__ void gemm_phase(const u16* __restrict__ A, const u16* __restrict__ Bt, const EpiArgs ea, char* smem, int tid) {
;     ...
;     for (int t = 0; t < nt; t += 2) {
;       const bool lastit = (t == nt - 2);
;       const u16* A2 = lastit ? Abn : Ab;
;       const u16* B2 = lastit ? Bbn : Bb;
;       const int k2 = lastit ? 0 : t + 2;
;       BODY(Ab, t + 1, A2, B2, k2, k2 + 1);
.LBB0_220:
	ds_read_b128 v[142:145], v135
	ds_read_b128 v[166:169], v139
	ds_read_b128 v[170:173], v135 offset:2048
	ds_read_b128 v[174:177], v139 offset:2048
	s_add_u32 s12, s10, 0xb0080
	s_addc_u32 s13, s11, 0
	s_add_u32 s14, s10, 0x108080
	s_addc_u32 s15, s11, 0
	s_cmp_eq_u32 s89, 40
	s_cselect_b32 s82, s5, s9
	s_cselect_b32 s83, s4, s8
	s_cselect_b32 s92, s3, s7
	s_cselect_b32 s93, s2, s6
	s_nop 0
	ds_read_b128 v[178:181], v136
	ds_read_b128 v[182:185], v137
	ds_read_b128 v[186:189], v136 offset:2048
	ds_read_b128 v[190:193], v137 offset:2048
	ds_read_b128 v[194:197], v136 offset:4096
	ds_read_b128 v[198:201], v137 offset:4096
	ds_read_b128 v[202:205], v136 offset:6144
	ds_read_b128 v[206:209], v137 offset:6144
	s_mov_b32 m0, s36
	s_nop 0
	global_load_lds_dwordx4 v130, s[12:13]
	s_nop 0
	s_mov_b32 m0, s37
	s_nop 0
	global_load_lds_dwordx4 v130, s[14:15]
	ds_read_b128 v[210:213], v135 offset:16384
	ds_read_b128 v[214:217], v139 offset:16384
	ds_read_b128 v[218:221], v135 offset:18432
	ds_read_b128 v[222:225], v139 offset:18432
	s_waitcnt vmcnt(8) lgkmcnt(0)
	s_barrier
	s_waitcnt lgkmcnt(7)
	v_mfma_f32_16x16x32_bf16 v[124:127], v[142:145], v[178:181], v[124:127]
	v_mfma_f32_16x16x32_bf16 v[120:123], v[170:173], v[178:181], v[120:123]
	s_waitcnt lgkmcnt(5)
	v_mfma_f32_16x16x32_bf16 v[88:91], v[218:221], v[178:181], v[88:91]
	v_mfma_f32_16x16x32_bf16 v[92:95], v[210:213], v[178:181], v[92:95]
	s_waitcnt lgkmcnt(3)
	v_mfma_f32_16x16x32_bf16 v[84:87], v[210:213], v[186:189], v[84:87]
	v_mfma_f32_16x16x32_bf16 v[80:83], v[218:221], v[186:189], v[80:83]
	s_waitcnt lgkmcnt(1)
	v_mfma_f32_16x16x32_bf16 v[112:115], v[170:173], v[186:189], v[112:115]
	v_mfma_f32_16x16x32_bf16 v[116:119], v[142:145], v[186:189], v[116:119]
	v_mfma_f32_16x16x32_bf16 v[108:111], v[142:145], v[194:197], v[108:111]
	v_mfma_f32_16x16x32_bf16 v[104:107], v[170:173], v[194:197], v[104:107]
	v_mfma_f32_16x16x32_bf16 v[72:75], v[218:221], v[194:197], v[72:75]
	v_mfma_f32_16x16x32_bf16 v[76:79], v[210:213], v[194:197], v[76:79]
	v_mfma_f32_16x16x32_bf16 v[68:71], v[210:213], v[202:205], v[68:71]
	v_mfma_f32_16x16x32_bf16 v[64:67], v[218:221], v[202:205], v[64:67]
	s_waitcnt lgkmcnt(0)
	v_mfma_f32_16x16x32_bf16 v[96:99], v[170:173], v[202:205], v[96:99]
	v_mfma_f32_16x16x32_bf16 v[100:103], v[142:145], v[202:205], v[100:103]
	s_waitcnt lgkmcnt(3)
	v_mfma_f32_16x16x32_bf16 v[100:103], v[166:169], v[206:209], v[100:103]
	s_waitcnt lgkmcnt(1)
	v_mfma_f32_16x16x32_bf16 v[96:99], v[174:177], v[206:209], v[96:99]
	v_mfma_f32_16x16x32_bf16 v[64:67], v[222:225], v[206:209], v[64:67]
	v_mfma_f32_16x16x32_bf16 v[68:71], v[214:217], v[206:209], v[68:71]
	v_mfma_f32_16x16x32_bf16 v[76:79], v[214:217], v[198:201], v[76:79]
	v_mfma_f32_16x16x32_bf16 v[72:75], v[222:225], v[198:201], v[72:75]
	v_mfma_f32_16x16x32_bf16 v[104:107], v[174:177], v[198:201], v[104:107]
	v_mfma_f32_16x16x32_bf16 v[108:111], v[166:169], v[198:201], v[108:111]
	v_mfma_f32_16x16x32_bf16 v[116:119], v[166:169], v[190:193], v[116:119]
	s_waitcnt lgkmcnt(0)
	v_mfma_f32_16x16x32_bf16 v[112:115], v[174:177], v[190:193], v[112:115]
	v_mfma_f32_16x16x32_bf16 v[80:83], v[222:225], v[190:193], v[80:83]
	v_mfma_f32_16x16x32_bf16 v[84:87], v[214:217], v[190:193], v[84:87]
	v_mfma_f32_16x16x32_bf16 v[92:95], v[214:217], v[182:185], v[92:95]
	v_mfma_f32_16x16x32_bf16 v[88:91], v[222:225], v[182:185], v[88:91]
	v_mfma_f32_16x16x32_bf16 v[120:123], v[174:177], v[182:185], v[120:123]
	v_mfma_f32_16x16x32_bf16 v[124:127], v[166:169], v[182:185], v[124:127]
	s_barrier
	s_cselect_b32 s70, 0, s94
	s_lshl_b64 s[96:97], s[70:71], 1
	s_add_u32 s12, s83, s96
	s_addc_u32 s13, s82, s97
	s_add_u32 s14, s12, 0x58000
	s_mov_b32 m0, s20
	s_nop 0
	global_load_lds_dwordx4 v130, s[12:13]
	s_addc_u32 s15, s13, 0
	s_mov_b32 m0, s21
	s_nop 0
	global_load_lds_dwordx4 v130, s[14:15]
	ds_read_b128 v[178:181], v136 offset:16384
	ds_read_b128 v[182:185], v137 offset:16384
	ds_read_b128 v[186:189], v136 offset:18432
	ds_read_b128 v[190:193], v137 offset:18432
	ds_read_b128 v[194:197], v136 offset:20480
	ds_read_b128 v[198:201], v137 offset:20480
	ds_read_b128 v[202:205], v136 offset:22528
	ds_read_b128 v[206:209], v137 offset:22528
	s_add_u32 s14, s93, s96
	s_addc_u32 s15, s92, s97
	s_add_u32 s92, s14, 0x58000
	s_mov_b32 m0, s19
	s_nop 0
	global_load_lds_dwordx4 v130, s[14:15]
	s_addc_u32 s93, s15, 0
	s_mov_b32 m0, s22
	s_nop 0
	global_load_lds_dwordx4 v130, s[92:93]
	s_add_u32 s83, s83, 0xb0000
	s_addc_u32 s82, s82, 0
	s_add_u32 s92, s83, s96
	s_addc_u32 s93, s82, s97
	s_add_u32 s96, s92, 0x58000
	s_mov_b32 m0, s23
	s_nop 0
	global_load_lds_dwordx4 v130, s[92:93]
	s_addc_u32 s97, s93, 0
	s_mov_b32 m0, s24
	s_nop 0
	global_load_lds_dwordx4 v130, s[96:97]
	s_waitcnt vmcnt(8) lgkmcnt(0)
	s_barrier
	s_waitcnt lgkmcnt(7)
	v_mfma_f32_16x16x32_bf16 v[60:63], v[142:145], v[178:181], v[60:63]
	v_mfma_f32_16x16x32_bf16 v[56:59], v[170:173], v[178:181], v[56:59]
	s_waitcnt lgkmcnt(5)
	v_mfma_f32_16x16x32_bf16 v[24:27], v[218:221], v[178:181], v[24:27]
	v_mfma_f32_16x16x32_bf16 v[28:31], v[210:213], v[178:181], v[28:31]
	s_waitcnt lgkmcnt(3)
	v_mfma_f32_16x16x32_bf16 v[20:23], v[210:213], v[186:189], v[20:23]
	v_mfma_f32_16x16x32_bf16 v[16:19], v[218:221], v[186:189], v[16:19]
	s_waitcnt lgkmcnt(1)
	v_mfma_f32_16x16x32_bf16 v[48:51], v[170:173], v[186:189], v[48:51]
	v_mfma_f32_16x16x32_bf16 v[52:55], v[142:145], v[186:189], v[52:55]
	v_mfma_f32_16x16x32_bf16 v[44:47], v[142:145], v[194:197], v[44:47]
	v_mfma_f32_16x16x32_bf16 v[40:43], v[170:173], v[194:197], v[40:43]
	v_mfma_f32_16x16x32_bf16 v[8:11], v[218:221], v[194:197], v[8:11]
	v_mfma_f32_16x16x32_bf16 v[12:15], v[210:213], v[194:197], v[12:15]
	v_mfma_f32_16x16x32_bf16 v[4:7], v[210:213], v[202:205], v[4:7]
	v_mfma_f32_16x16x32_bf16 v[0:3], v[218:221], v[202:205], v[0:3]
	s_waitcnt lgkmcnt(0)
	v_mfma_f32_16x16x32_bf16 v[32:35], v[170:173], v[202:205], v[32:35]
	v_mfma_f32_16x16x32_bf16 v[36:39], v[142:145], v[202:205], v[36:39]
	v_mfma_f32_16x16x32_bf16 v[36:39], v[166:169], v[206:209], v[36:39]
	v_mfma_f32_16x16x32_bf16 v[32:35], v[174:177], v[206:209], v[32:35]
	v_mfma_f32_16x16x32_bf16 v[0:3], v[222:225], v[206:209], v[0:3]
	v_mfma_f32_16x16x32_bf16 v[4:7], v[214:217], v[206:209], v[4:7]
	v_mfma_f32_16x16x32_bf16 v[12:15], v[214:217], v[198:201], v[12:15]
	v_mfma_f32_16x16x32_bf16 v[8:11], v[222:225], v[198:201], v[8:11]
	v_mfma_f32_16x16x32_bf16 v[40:43], v[174:177], v[198:201], v[40:43]
	v_mfma_f32_16x16x32_bf16 v[44:47], v[166:169], v[198:201], v[44:47]
	v_mfma_f32_16x16x32_bf16 v[52:55], v[166:169], v[190:193], v[52:55]
	v_mfma_f32_16x16x32_bf16 v[48:51], v[174:177], v[190:193], v[48:51]
	v_mfma_f32_16x16x32_bf16 v[16:19], v[222:225], v[190:193], v[16:19]
	v_mfma_f32_16x16x32_bf16 v[20:23], v[214:217], v[190:193], v[20:23]
	v_mfma_f32_16x16x32_bf16 v[28:31], v[214:217], v[182:185], v[28:31]
	v_mfma_f32_16x16x32_bf16 v[24:27], v[222:225], v[182:185], v[24:27]
	v_mfma_f32_16x16x32_bf16 v[56:59], v[174:177], v[182:185], v[56:59]
	v_mfma_f32_16x16x32_bf16 v[60:63], v[166:169], v[182:185], v[60:63]
	s_barrier
	ds_read_b128 v[142:145], v135 offset:32768
	ds_read_b128 v[166:169], v139 offset:32768
	ds_read_b128 v[170:173], v135 offset:34816
	ds_read_b128 v[174:177], v139 offset:34816
	ds_read_b128 v[178:181], v136 offset:32768
	ds_read_b128 v[182:185], v137 offset:32768
	ds_read_b128 v[186:189], v136 offset:34816
	ds_read_b128 v[190:193], v137 offset:34816
	ds_read_b128 v[194:197], v136 offset:36864
	ds_read_b128 v[198:201], v137 offset:36864
	ds_read_b128 v[202:205], v136 offset:38912
	ds_read_b128 v[206:209], v137 offset:38912
	s_add_u32 s92, s14, 0xb0000
	s_addc_u32 s93, s15, 0
	s_add_u32 s96, s14, 0x108000
	s_mov_b32 m0, s25
	s_nop 0
	global_load_lds_dwordx4 v130, s[92:93]
	s_addc_u32 s97, s15, 0
	s_mov_b32 m0, s26
	s_nop 0
	global_load_lds_dwordx4 v130, s[96:97]
	ds_read_b128 v[210:213], v135 offset:49152
	ds_read_b128 v[214:217], v139 offset:49152
	ds_read_b128 v[218:221], v135 offset:51200
	ds_read_b128 v[222:225], v139 offset:51200
	s_waitcnt vmcnt(8) lgkmcnt(0)
	s_barrier
	s_waitcnt lgkmcnt(7)
	v_mfma_f32_16x16x32_bf16 v[124:127], v[142:145], v[178:181], v[124:127]
	v_mfma_f32_16x16x32_bf16 v[120:123], v[170:173], v[178:181], v[120:123]
	s_waitcnt lgkmcnt(5)
	v_mfma_f32_16x16x32_bf16 v[88:91], v[218:221], v[178:181], v[88:91]
	v_mfma_f32_16x16x32_bf16 v[92:95], v[210:213], v[178:181], v[92:95]
	s_waitcnt lgkmcnt(3)
	v_mfma_f32_16x16x32_bf16 v[84:87], v[210:213], v[186:189], v[84:87]
	v_mfma_f32_16x16x32_bf16 v[80:83], v[218:221], v[186:189], v[80:83]
	s_waitcnt lgkmcnt(1)
	v_mfma_f32_16x16x32_bf16 v[112:115], v[170:173], v[186:189], v[112:115]
	v_mfma_f32_16x16x32_bf16 v[116:119], v[142:145], v[186:189], v[116:119]
	v_mfma_f32_16x16x32_bf16 v[108:111], v[142:145], v[194:197], v[108:111]
	v_mfma_f32_16x16x32_bf16 v[104:107], v[170:173], v[194:197], v[104:107]
	v_mfma_f32_16x16x32_bf16 v[72:75], v[218:221], v[194:197], v[72:75]
	v_mfma_f32_16x16x32_bf16 v[76:79], v[210:213], v[194:197], v[76:79]
	v_mfma_f32_16x16x32_bf16 v[68:71], v[210:213], v[202:205], v[68:71]
	v_mfma_f32_16x16x32_bf16 v[64:67], v[218:221], v[202:205], v[64:67]
	s_waitcnt lgkmcnt(0)
	v_mfma_f32_16x16x32_bf16 v[96:99], v[170:173], v[202:205], v[96:99]
	v_mfma_f32_16x16x32_bf16 v[100:103], v[142:145], v[202:205], v[100:103]
	s_waitcnt lgkmcnt(3)
	v_mfma_f32_16x16x32_bf16 v[100:103], v[166:169], v[206:209], v[100:103]
	s_waitcnt lgkmcnt(1)
	v_mfma_f32_16x16x32_bf16 v[96:99], v[174:177], v[206:209], v[96:99]
	v_mfma_f32_16x16x32_bf16 v[64:67], v[222:225], v[206:209], v[64:67]
	v_mfma_f32_16x16x32_bf16 v[68:71], v[214:217], v[206:209], v[68:71]
	v_mfma_f32_16x16x32_bf16 v[76:79], v[214:217], v[198:201], v[76:79]
	v_mfma_f32_16x16x32_bf16 v[72:75], v[222:225], v[198:201], v[72:75]
	v_mfma_f32_16x16x32_bf16 v[104:107], v[174:177], v[198:201], v[104:107]
	v_mfma_f32_16x16x32_bf16 v[108:111], v[166:169], v[198:201], v[108:111]
	v_mfma_f32_16x16x32_bf16 v[116:119], v[166:169], v[190:193], v[116:119]
	s_waitcnt lgkmcnt(0)
	v_mfma_f32_16x16x32_bf16 v[112:115], v[174:177], v[190:193], v[112:115]
	v_mfma_f32_16x16x32_bf16 v[80:83], v[222:225], v[190:193], v[80:83]
	v_mfma_f32_16x16x32_bf16 v[84:87], v[214:217], v[190:193], v[84:87]
	v_mfma_f32_16x16x32_bf16 v[92:95], v[214:217], v[182:185], v[92:95]
	v_mfma_f32_16x16x32_bf16 v[88:91], v[222:225], v[182:185], v[88:91]
	v_mfma_f32_16x16x32_bf16 v[120:123], v[174:177], v[182:185], v[120:123]
	v_mfma_f32_16x16x32_bf16 v[124:127], v[166:169], v[182:185], v[124:127]
	s_barrier
; template <int N, int K, int EPI>
; __device__ void gemm_phase(const u16* __restrict__ A, const u16* __restrict__ Bt, const EpiArgs ea, char* smem, int tid) {
;     ...
;     for (int t = 0; t < nt; t += 2) {
	s_or_b32 s70, s70, 64
	s_add_u32 s92, s12, 0x80
	s_addc_u32 s93, s13, 0
	s_add_u32 s12, s12, 0x58080
	s_mov_b32 m0, s27
	s_nop 0
	global_load_lds_dwordx4 v130, s[92:93]
	s_addc_u32 s13, s13, 0
	s_mov_b32 m0, s28
	s_nop 0
	global_load_lds_dwordx4 v130, s[12:13]
	ds_read_b128 v[178:181], v136 offset:49152
	ds_read_b128 v[182:185], v137 offset:49152
	ds_read_b128 v[186:189], v136 offset:51200
	ds_read_b128 v[190:193], v137 offset:51200
	ds_read_b128 v[194:197], v136 offset:53248
	ds_read_b128 v[198:201], v137 offset:53248
	ds_read_b128 v[202:205], v136 offset:55296
	ds_read_b128 v[206:209], v137 offset:55296
	s_add_u32 s12, s14, 0x80
	s_addc_u32 s13, s15, 0
	s_add_u32 s14, s14, 0x58080
	s_mov_b32 m0, s29
	s_nop 0
	global_load_lds_dwordx4 v130, s[12:13]
	s_addc_u32 s15, s15, 0
	s_mov_b32 m0, s30
	s_nop 0
	global_load_lds_dwordx4 v130, s[14:15]
	s_lshl_b64 s[12:13], s[70:71], 1
	s_add_u32 s12, s83, s12
	s_addc_u32 s13, s82, s13
	s_add_u32 s14, s12, 0x58000
	s_mov_b32 m0, s31
	s_nop 0
	global_load_lds_dwordx4 v130, s[12:13]
	s_addc_u32 s15, s13, 0
	s_mov_b32 m0, s34
	s_nop 0
	global_load_lds_dwordx4 v130, s[14:15]
	s_waitcnt vmcnt(8) lgkmcnt(0)
	s_barrier
	s_waitcnt lgkmcnt(7)
	v_mfma_f32_16x16x32_bf16 v[60:63], v[142:145], v[178:181], v[60:63]
	v_mfma_f32_16x16x32_bf16 v[56:59], v[170:173], v[178:181], v[56:59]
	s_waitcnt lgkmcnt(5)
	v_mfma_f32_16x16x32_bf16 v[24:27], v[218:221], v[178:181], v[24:27]
	v_mfma_f32_16x16x32_bf16 v[28:31], v[210:213], v[178:181], v[28:31]
	s_waitcnt lgkmcnt(3)
	v_mfma_f32_16x16x32_bf16 v[20:23], v[210:213], v[186:189], v[20:23]
	v_mfma_f32_16x16x32_bf16 v[16:19], v[218:221], v[186:189], v[16:19]
	s_waitcnt lgkmcnt(1)
	v_mfma_f32_16x16x32_bf16 v[48:51], v[170:173], v[186:189], v[48:51]
	v_mfma_f32_16x16x32_bf16 v[52:55], v[142:145], v[186:189], v[52:55]
	v_mfma_f32_16x16x32_bf16 v[44:47], v[142:145], v[194:197], v[44:47]
	v_mfma_f32_16x16x32_bf16 v[40:43], v[170:173], v[194:197], v[40:43]
	v_mfma_f32_16x16x32_bf16 v[8:11], v[218:221], v[194:197], v[8:11]
	v_mfma_f32_16x16x32_bf16 v[12:15], v[210:213], v[194:197], v[12:15]
	v_mfma_f32_16x16x32_bf16 v[4:7], v[210:213], v[202:205], v[4:7]
	v_mfma_f32_16x16x32_bf16 v[0:3], v[218:221], v[202:205], v[0:3]
	s_waitcnt lgkmcnt(0)
	v_mfma_f32_16x16x32_bf16 v[32:35], v[170:173], v[202:205], v[32:35]
	v_mfma_f32_16x16x32_bf16 v[36:39], v[142:145], v[202:205], v[36:39]
	v_mfma_f32_16x16x32_bf16 v[36:39], v[166:169], v[206:209], v[36:39]
	v_mfma_f32_16x16x32_bf16 v[32:35], v[174:177], v[206:209], v[32:35]
	v_mfma_f32_16x16x32_bf16 v[0:3], v[222:225], v[206:209], v[0:3]
	v_mfma_f32_16x16x32_bf16 v[4:7], v[214:217], v[206:209], v[4:7]
	v_mfma_f32_16x16x32_bf16 v[12:15], v[214:217], v[198:201], v[12:15]
	v_mfma_f32_16x16x32_bf16 v[8:11], v[222:225], v[198:201], v[8:11]
	v_mfma_f32_16x16x32_bf16 v[40:43], v[174:177], v[198:201], v[40:43]
	v_mfma_f32_16x16x32_bf16 v[44:47], v[166:169], v[198:201], v[44:47]
	v_mfma_f32_16x16x32_bf16 v[52:55], v[166:169], v[190:193], v[52:55]
	v_mfma_f32_16x16x32_bf16 v[48:51], v[174:177], v[190:193], v[48:51]
	v_mfma_f32_16x16x32_bf16 v[16:19], v[222:225], v[190:193], v[16:19]
	v_mfma_f32_16x16x32_bf16 v[20:23], v[214:217], v[190:193], v[20:23]
	v_mfma_f32_16x16x32_bf16 v[28:31], v[214:217], v[182:185], v[28:31]
	v_mfma_f32_16x16x32_bf16 v[24:27], v[222:225], v[182:185], v[24:27]
	v_mfma_f32_16x16x32_bf16 v[56:59], v[174:177], v[182:185], v[56:59]
	v_mfma_f32_16x16x32_bf16 v[60:63], v[166:169], v[182:185], v[60:63]
	s_add_i32 s89, s89, 2
	s_addk_i32 s94, 0x80
	s_add_u32 s10, s10, 0x100
	s_addc_u32 s11, s11, 0
	s_cmp_gt_u32 s89, 41
	s_barrier
	s_cbranch_scc0 .LBB0_220
; #define WAIT_V(n) asm volatile("s_waitcnt vmcnt(" #n ")" ::: "memory")
; #define BAR __builtin_amdgcn_s_barrier()
; template <int N, int K, int EPI>
; __device__ void gemm_phase(const u16* __restrict__ A, const u16* __restrict__ Bt, const EpiArgs ea, char* smem, int tid) {
;     ...
;       } else if constexpr (EPI == EPI_F) {
;         u16* f = ea.o0;
; #pragma unroll
;         for (int ai = 0; ai < 2; ++ai)
; #pragma unroll
;           for (int bj = 0; bj < 2; ++bj)
; #pragma unroll
;             for (int m = 0; m < 4; ++m) {
;               const int row = brow + ai * HALF + wr * 64 + m * 16 + fr_e;
;               const int col = pn * BM + bj * HALF + wc * 32 + fq_e * 8;
;               const f32x4 v0 = acc[ai][bj][m][0], v1 = acc[ai][bj][m][1];
;               u32x4 o = {pk_bf16(v0[0], v0[1]), pk_bf16(v0[2], v0[3]), pk_bf16(v1[0], v1[1]), pk_bf16(v1[2], v1[3])};
;               *(u32x4*)(f + (size_t)row * N + col) = o;
;             }
;     ...
;     if (!has_next) break;
; #pragma unroll
;     for (int ai = 0; ai < 2; ++ai)
; #pragma unroll
;       for (int bj = 0; bj < 2; ++bj)
; #pragma unroll
;         for (int m = 0; m < 4; ++m)
; #pragma unroll
;           for (int n = 0; n < 2; ++n) acc[ai][bj][m][n] = f32x4{0.f, 0.f, 0.f, 0.f};
;     v = vn; pm = pmn; pn = pnn; Ab = Abn; Bb = Bbn;
;   }
;   WAIT_V(0);
;   if (wr == 0) BAR;
	s_lshl_b32 s6, s88, 8
	v_mov_b32_e32 v128, v131
	v_mov_b32_e32 v129, v132
	s_add_i32 s6, s6, s35
	v_cvt_pk_bf16_f32 v124, v124, v125
	v_cvt_pk_bf16_f32 v125, v126, v127
	v_cvt_pk_bf16_f32 v126, v120, v121
	v_cvt_pk_bf16_f32 v127, v122, v123
	v_cvt_pk_bf16_f32 v116, v116, v117
	s_nop 0
	v_add_u32_e32 v142, s6, v128
	s_lshl_b32 s6, s73, 8
	s_or_b32 s6, s6, s42
	v_lshl_add_u32 v144, v129, 3, s6
	v_ashrrev_i32_e32 v145, 31, v144
	v_ashrrev_i32_e32 v143, 31, v142
	v_lshl_add_u64 v[128:129], v[144:145], 1, s[64:65]
	v_lshlrev_b64 v[120:121], 11, v[142:143]
	v_lshl_add_u64 v[122:123], v[128:129], 0, v[120:121]
	global_store_dwordx4 v[122:123], v[124:127], off
	v_add_u32_e32 v122, 16, v142
	v_ashrrev_i32_e32 v123, 31, v122
	v_cvt_pk_bf16_f32 v117, v118, v119
	v_cvt_pk_bf16_f32 v118, v112, v113
	v_lshlrev_b64 v[112:113], 11, v[122:123]
	v_cvt_pk_bf16_f32 v119, v114, v115
	v_lshl_add_u64 v[114:115], v[128:129], 0, v[112:113]
	global_store_dwordx4 v[114:115], v[116:119], off
	v_add_u32_e32 v114, 32, v142
	v_ashrrev_i32_e32 v115, 31, v114
	v_cvt_pk_bf16_f32 v108, v108, v109
	v_cvt_pk_bf16_f32 v109, v110, v111
	v_cvt_pk_bf16_f32 v110, v104, v105
	v_lshlrev_b64 v[104:105], 11, v[114:115]
	v_cvt_pk_bf16_f32 v111, v106, v107
	v_lshl_add_u64 v[106:107], v[128:129], 0, v[104:105]
	global_store_dwordx4 v[106:107], v[108:111], off
	v_add_u32_e32 v106, 48, v142
	v_ashrrev_i32_e32 v107, 31, v106
	v_cvt_pk_bf16_f32 v100, v100, v101
	v_cvt_pk_bf16_f32 v101, v102, v103
	v_cvt_pk_bf16_f32 v102, v96, v97
	v_lshlrev_b64 v[96:97], 11, v[106:107]
	v_cvt_pk_bf16_f32 v103, v98, v99
	v_lshl_add_u64 v[98:99], v[128:129], 0, v[96:97]
	global_store_dwordx4 v[98:99], v[100:103], off
	v_add_u32_e32 v98, 0x80, v144
	v_ashrrev_i32_e32 v99, 31, v98
	v_lshl_add_u64 v[98:99], v[98:99], 1, s[64:65]
	v_cvt_pk_bf16_f32 v68, v68, v69
	v_cvt_pk_bf16_f32 v69, v70, v71
	v_cvt_pk_bf16_f32 v70, v64, v65
	v_lshl_add_u64 v[64:65], v[98:99], 0, v[96:97]
	v_cvt_pk_bf16_f32 v71, v66, v67
	global_store_dwordx4 v[64:65], v[68:71], off
	v_add_u32_e32 v64, 0x80, v142
	v_ashrrev_i32_e32 v65, 31, v64
	v_cvt_pk_bf16_f32 v60, v60, v61
	v_cvt_pk_bf16_f32 v61, v62, v63
	v_cvt_pk_bf16_f32 v62, v56, v57
	v_lshlrev_b64 v[56:57], 11, v[64:65]
	v_cvt_pk_bf16_f32 v92, v92, v93
	v_cvt_pk_bf16_f32 v93, v94, v95
	v_cvt_pk_bf16_f32 v94, v88, v89
	v_lshl_add_u64 v[88:89], v[98:99], 0, v[120:121]
	v_cvt_pk_bf16_f32 v84, v84, v85
	v_cvt_pk_bf16_f32 v85, v86, v87
	v_cvt_pk_bf16_f32 v86, v80, v81
	v_lshl_add_u64 v[80:81], v[98:99], 0, v[112:113]
	v_cvt_pk_bf16_f32 v76, v76, v77
	v_cvt_pk_bf16_f32 v77, v78, v79
	v_cvt_pk_bf16_f32 v78, v72, v73
	v_lshl_add_u64 v[72:73], v[98:99], 0, v[104:105]
	v_cvt_pk_bf16_f32 v63, v58, v59
	v_lshl_add_u64 v[58:59], v[128:129], 0, v[56:57]
	v_cvt_pk_bf16_f32 v95, v90, v91
	global_store_dwordx4 v[88:89], v[92:95], off
	v_cvt_pk_bf16_f32 v87, v82, v83
	global_store_dwordx4 v[80:81], v[84:87], off
	v_cvt_pk_bf16_f32 v79, v74, v75
	global_store_dwordx4 v[72:73], v[76:79], off
	global_store_dwordx4 v[58:59], v[60:63], off
	v_add_u32_e32 v58, 0x90, v142
	v_ashrrev_i32_e32 v59, 31, v58
	v_cvt_pk_bf16_f32 v52, v52, v53
	v_cvt_pk_bf16_f32 v53, v54, v55
	v_cvt_pk_bf16_f32 v54, v48, v49
	v_lshlrev_b64 v[48:49], 11, v[58:59]
	v_cvt_pk_bf16_f32 v55, v50, v51
	v_lshl_add_u64 v[50:51], v[128:129], 0, v[48:49]
	global_store_dwordx4 v[50:51], v[52:55], off
	v_add_u32_e32 v50, 0xa0, v142
	v_ashrrev_i32_e32 v51, 31, v50
	v_cvt_pk_bf16_f32 v44, v44, v45
	v_cvt_pk_bf16_f32 v45, v46, v47
	v_cvt_pk_bf16_f32 v46, v40, v41
	v_lshlrev_b64 v[40:41], 11, v[50:51]
	v_cvt_pk_bf16_f32 v47, v42, v43
	v_lshl_add_u64 v[42:43], v[128:129], 0, v[40:41]
	global_store_dwordx4 v[42:43], v[44:47], off
	v_add_u32_e32 v42, 0xb0, v142
	v_ashrrev_i32_e32 v43, 31, v42
	v_cvt_pk_bf16_f32 v36, v36, v37
	v_cvt_pk_bf16_f32 v37, v38, v39
	v_cvt_pk_bf16_f32 v38, v32, v33
	v_lshlrev_b64 v[32:33], 11, v[42:43]
	v_cvt_pk_bf16_f32 v39, v34, v35
	v_lshl_add_u64 v[34:35], v[128:129], 0, v[32:33]
	v_cvt_pk_bf16_f32 v28, v28, v29
	v_cvt_pk_bf16_f32 v29, v30, v31
	v_cvt_pk_bf16_f32 v30, v24, v25
	v_lshl_add_u64 v[24:25], v[98:99], 0, v[56:57]
	v_cvt_pk_bf16_f32 v20, v20, v21
	v_cvt_pk_bf16_f32 v21, v22, v23
	v_cvt_pk_bf16_f32 v22, v16, v17
	v_lshl_add_u64 v[16:17], v[98:99], 0, v[48:49]
	v_cvt_pk_bf16_f32 v12, v12, v13
	v_cvt_pk_bf16_f32 v13, v14, v15
	v_cvt_pk_bf16_f32 v14, v8, v9
	v_lshl_add_u64 v[8:9], v[98:99], 0, v[40:41]
	v_cvt_pk_bf16_f32 v4, v4, v5
	v_cvt_pk_bf16_f32 v5, v6, v7
	v_cvt_pk_bf16_f32 v6, v0, v1
	v_lshl_add_u64 v[0:1], v[98:99], 0, v[32:33]
	s_and_b64 vcc, exec, s[0:1]
	s_mov_b32 s88, s67
	s_mov_b32 s73, s72
	s_mov_b64 s[8:9], s[4:5]
	s_mov_b64 s[6:7], s[2:3]
	global_store_dwordx4 v[34:35], v[36:39], off
	v_cvt_pk_bf16_f32 v31, v26, v27
	global_store_dwordx4 v[24:25], v[28:31], off
	v_cvt_pk_bf16_f32 v23, v18, v19
	global_store_dwordx4 v[16:17], v[20:23], off
	v_cvt_pk_bf16_f32 v15, v10, v11
	global_store_dwordx4 v[8:9], v[12:15], off
	v_cvt_pk_bf16_f32 v7, v2, v3
	global_store_dwordx4 v[0:1], v[4:7], off
	s_cbranch_vccz .LBB0_217
	s_setprio 0
	s_waitcnt vmcnt(0)
	v_readlane_b32 s34, v226, 32
	v_readlane_b32 s36, v226, 30
	s_cmpk_gt_u32 s18, 0xff
	s_movk_i32 s27, 0x7fff
	s_mov_b32 s28, 0x800000
	s_mov_b32 s29, 0xa000000
	s_mov_b32 s30, 0x41000
	v_readlane_b32 s35, v226, 33
	v_readlane_b32 s37, v226, 31
	s_cbranch_scc1 .LBB0_224
	s_barrier

.LBB0_236:
	ds_read_b128 v[142:145], v135
	ds_read_b128 v[166:169], v139
	ds_read_b128 v[170:173], v135 offset:2048
	ds_read_b128 v[174:177], v139 offset:2048
	s_add_u32 s16, s14, 0x40080
	s_addc_u32 s17, s15, 0
	s_add_u32 s18, s14, 0x60080
	s_addc_u32 s19, s15, 0
	s_cmp_eq_u32 s3, 12
	s_cselect_b32 s82, s9, s13
	s_cselect_b32 s83, s8, s12
	s_cselect_b32 s92, s7, s11
	s_cselect_b32 s93, s6, s10
	s_nop 0
	ds_read_b128 v[178:181], v136
	ds_read_b128 v[182:185], v137
	ds_read_b128 v[186:189], v136 offset:2048
	ds_read_b128 v[190:193], v137 offset:2048
	ds_read_b128 v[194:197], v136 offset:4096
	ds_read_b128 v[198:201], v137 offset:4096
	ds_read_b128 v[202:205], v136 offset:6144
	ds_read_b128 v[206:209], v137 offset:6144
	s_mov_b32 m0, s64
	s_nop 0
	global_load_lds_dwordx4 v130, s[16:17]
	s_nop 0
	s_mov_b32 m0, s65
	s_nop 0
	global_load_lds_dwordx4 v130, s[18:19]
	ds_read_b128 v[210:213], v135 offset:16384
	ds_read_b128 v[214:217], v139 offset:16384
	ds_read_b128 v[218:221], v135 offset:18432
	ds_read_b128 v[222:225], v139 offset:18432
	s_waitcnt vmcnt(8) lgkmcnt(0)
	s_barrier
	s_waitcnt lgkmcnt(7)
	v_mfma_f32_16x16x32_bf16 v[124:127], v[142:145], v[178:181], v[124:127]
	v_mfma_f32_16x16x32_bf16 v[116:119], v[170:173], v[178:181], v[116:119]
	s_waitcnt lgkmcnt(5)
	v_mfma_f32_16x16x32_bf16 v[112:115], v[218:221], v[178:181], v[112:115]
	v_mfma_f32_16x16x32_bf16 v[120:123], v[210:213], v[178:181], v[120:123]
	s_waitcnt lgkmcnt(3)
	v_mfma_f32_16x16x32_bf16 v[104:107], v[210:213], v[186:189], v[104:107]
	v_mfma_f32_16x16x32_bf16 v[96:99], v[218:221], v[186:189], v[96:99]
	s_waitcnt lgkmcnt(1)
	v_mfma_f32_16x16x32_bf16 v[100:103], v[170:173], v[186:189], v[100:103]
	v_mfma_f32_16x16x32_bf16 v[108:111], v[142:145], v[186:189], v[108:111]
	v_mfma_f32_16x16x32_bf16 v[92:95], v[142:145], v[194:197], v[92:95]
	v_mfma_f32_16x16x32_bf16 v[84:87], v[170:173], v[194:197], v[84:87]
	v_mfma_f32_16x16x32_bf16 v[80:83], v[218:221], v[194:197], v[80:83]
	v_mfma_f32_16x16x32_bf16 v[88:91], v[210:213], v[194:197], v[88:91]
	v_mfma_f32_16x16x32_bf16 v[72:75], v[210:213], v[202:205], v[72:75]
	v_mfma_f32_16x16x32_bf16 v[64:67], v[218:221], v[202:205], v[64:67]
	s_waitcnt lgkmcnt(0)
	v_mfma_f32_16x16x32_bf16 v[68:71], v[170:173], v[202:205], v[68:71]
	v_mfma_f32_16x16x32_bf16 v[76:79], v[142:145], v[202:205], v[76:79]
	s_waitcnt lgkmcnt(3)
	v_mfma_f32_16x16x32_bf16 v[76:79], v[166:169], v[206:209], v[76:79]
	s_waitcnt lgkmcnt(1)
	v_mfma_f32_16x16x32_bf16 v[68:71], v[174:177], v[206:209], v[68:71]
	v_mfma_f32_16x16x32_bf16 v[64:67], v[222:225], v[206:209], v[64:67]
	v_mfma_f32_16x16x32_bf16 v[72:75], v[214:217], v[206:209], v[72:75]
	v_mfma_f32_16x16x32_bf16 v[88:91], v[214:217], v[198:201], v[88:91]
	v_mfma_f32_16x16x32_bf16 v[80:83], v[222:225], v[198:201], v[80:83]
	v_mfma_f32_16x16x32_bf16 v[84:87], v[174:177], v[198:201], v[84:87]
	v_mfma_f32_16x16x32_bf16 v[92:95], v[166:169], v[198:201], v[92:95]
	v_mfma_f32_16x16x32_bf16 v[108:111], v[166:169], v[190:193], v[108:111]
	s_waitcnt lgkmcnt(0)
	v_mfma_f32_16x16x32_bf16 v[100:103], v[174:177], v[190:193], v[100:103]
	v_mfma_f32_16x16x32_bf16 v[96:99], v[222:225], v[190:193], v[96:99]
	v_mfma_f32_16x16x32_bf16 v[104:107], v[214:217], v[190:193], v[104:107]
	v_mfma_f32_16x16x32_bf16 v[120:123], v[214:217], v[182:185], v[120:123]
	v_mfma_f32_16x16x32_bf16 v[112:115], v[222:225], v[182:185], v[112:115]
	v_mfma_f32_16x16x32_bf16 v[116:119], v[174:177], v[182:185], v[116:119]
	v_mfma_f32_16x16x32_bf16 v[124:127], v[166:169], v[182:185], v[124:127]
	s_barrier
	s_cselect_b32 s70, 0, s5
	s_lshl_b64 s[88:89], s[70:71], 1
	s_add_u32 s16, s83, s88
	s_addc_u32 s17, s82, s89
	s_add_u32 s18, s16, 0x20000
	s_mov_b32 m0, s24
	s_nop 0
	global_load_lds_dwordx4 v130, s[16:17]
	s_addc_u32 s19, s17, 0
	s_mov_b32 m0, s25
	s_nop 0
	global_load_lds_dwordx4 v130, s[18:19]
	ds_read_b128 v[178:181], v136 offset:16384
	ds_read_b128 v[182:185], v137 offset:16384
	ds_read_b128 v[186:189], v136 offset:18432
	ds_read_b128 v[190:193], v137 offset:18432
	ds_read_b128 v[194:197], v136 offset:20480
	ds_read_b128 v[198:201], v137 offset:20480
	ds_read_b128 v[202:205], v136 offset:22528
	ds_read_b128 v[206:209], v137 offset:22528
	s_add_u32 s18, s93, s88
	s_addc_u32 s19, s92, s89
	s_add_u32 s94, s18, 0x20000
	s_mov_b32 m0, s23
	s_nop 0
	global_load_lds_dwordx4 v130, s[18:19]
	s_addc_u32 s95, s19, 0
	s_mov_b32 m0, s26
	s_nop 0
	global_load_lds_dwordx4 v130, s[94:95]
	s_add_u32 s83, s83, 0x40000
	s_addc_u32 s82, s82, 0
	s_add_u32 s88, s83, s88
	s_addc_u32 s89, s82, s89
	s_add_u32 s94, s88, 0x20000
	s_mov_b32 m0, s27
	s_nop 0
	global_load_lds_dwordx4 v130, s[88:89]
	s_addc_u32 s95, s89, 0
	s_mov_b32 m0, s28
	s_nop 0
	global_load_lds_dwordx4 v130, s[94:95]
	s_waitcnt vmcnt(8) lgkmcnt(0)
	s_barrier
	s_waitcnt lgkmcnt(7)
	v_mfma_f32_16x16x32_bf16 v[60:63], v[142:145], v[178:181], v[60:63]
	v_mfma_f32_16x16x32_bf16 v[52:55], v[170:173], v[178:181], v[52:55]
	s_waitcnt lgkmcnt(5)
	v_mfma_f32_16x16x32_bf16 v[48:51], v[218:221], v[178:181], v[48:51]
	v_mfma_f32_16x16x32_bf16 v[56:59], v[210:213], v[178:181], v[56:59]
	s_waitcnt lgkmcnt(3)
	v_mfma_f32_16x16x32_bf16 v[40:43], v[210:213], v[186:189], v[40:43]
	v_mfma_f32_16x16x32_bf16 v[32:35], v[218:221], v[186:189], v[32:35]
	s_waitcnt lgkmcnt(1)
	v_mfma_f32_16x16x32_bf16 v[36:39], v[170:173], v[186:189], v[36:39]
	v_mfma_f32_16x16x32_bf16 v[44:47], v[142:145], v[186:189], v[44:47]
	v_mfma_f32_16x16x32_bf16 v[28:31], v[142:145], v[194:197], v[28:31]
	v_mfma_f32_16x16x32_bf16 v[20:23], v[170:173], v[194:197], v[20:23]
	v_mfma_f32_16x16x32_bf16 v[16:19], v[218:221], v[194:197], v[16:19]
	v_mfma_f32_16x16x32_bf16 v[24:27], v[210:213], v[194:197], v[24:27]
	v_mfma_f32_16x16x32_bf16 v[8:11], v[210:213], v[202:205], v[8:11]
	v_mfma_f32_16x16x32_bf16 v[0:3], v[218:221], v[202:205], v[0:3]
	s_waitcnt lgkmcnt(0)
	v_mfma_f32_16x16x32_bf16 v[4:7], v[170:173], v[202:205], v[4:7]
	v_mfma_f32_16x16x32_bf16 v[12:15], v[142:145], v[202:205], v[12:15]
	v_mfma_f32_16x16x32_bf16 v[12:15], v[166:169], v[206:209], v[12:15]
	v_mfma_f32_16x16x32_bf16 v[4:7], v[174:177], v[206:209], v[4:7]
	v_mfma_f32_16x16x32_bf16 v[0:3], v[222:225], v[206:209], v[0:3]
	v_mfma_f32_16x16x32_bf16 v[8:11], v[214:217], v[206:209], v[8:11]
	v_mfma_f32_16x16x32_bf16 v[24:27], v[214:217], v[198:201], v[24:27]
	v_mfma_f32_16x16x32_bf16 v[16:19], v[222:225], v[198:201], v[16:19]
	v_mfma_f32_16x16x32_bf16 v[20:23], v[174:177], v[198:201], v[20:23]
	v_mfma_f32_16x16x32_bf16 v[28:31], v[166:169], v[198:201], v[28:31]
	v_mfma_f32_16x16x32_bf16 v[44:47], v[166:169], v[190:193], v[44:47]
	v_mfma_f32_16x16x32_bf16 v[36:39], v[174:177], v[190:193], v[36:39]
	v_mfma_f32_16x16x32_bf16 v[32:35], v[222:225], v[190:193], v[32:35]
	v_mfma_f32_16x16x32_bf16 v[40:43], v[214:217], v[190:193], v[40:43]
	v_mfma_f32_16x16x32_bf16 v[56:59], v[214:217], v[182:185], v[56:59]
	v_mfma_f32_16x16x32_bf16 v[48:51], v[222:225], v[182:185], v[48:51]
	v_mfma_f32_16x16x32_bf16 v[52:55], v[174:177], v[182:185], v[52:55]
	v_mfma_f32_16x16x32_bf16 v[60:63], v[166:169], v[182:185], v[60:63]
	s_barrier
	ds_read_b128 v[142:145], v135 offset:32768
	ds_read_b128 v[166:169], v139 offset:32768
	ds_read_b128 v[170:173], v135 offset:34816
	ds_read_b128 v[174:177], v139 offset:34816
	ds_read_b128 v[178:181], v136 offset:32768
	ds_read_b128 v[182:185], v137 offset:32768
	ds_read_b128 v[186:189], v136 offset:34816
	ds_read_b128 v[190:193], v137 offset:34816
	ds_read_b128 v[194:197], v136 offset:36864
	ds_read_b128 v[198:201], v137 offset:36864
	ds_read_b128 v[202:205], v136 offset:38912
	ds_read_b128 v[206:209], v137 offset:38912
	s_add_u32 s88, s18, 0x40000
	s_addc_u32 s89, s19, 0
	s_add_u32 s94, s18, 0x60000
	s_mov_b32 m0, s29
	s_nop 0
	global_load_lds_dwordx4 v130, s[88:89]
	s_addc_u32 s95, s19, 0
	s_mov_b32 m0, s30
	s_nop 0
	global_load_lds_dwordx4 v130, s[94:95]
	ds_read_b128 v[210:213], v135 offset:49152
	ds_read_b128 v[214:217], v139 offset:49152
	ds_read_b128 v[218:221], v135 offset:51200
	ds_read_b128 v[222:225], v139 offset:51200
	s_waitcnt vmcnt(8) lgkmcnt(0)
	s_barrier
	s_waitcnt lgkmcnt(7)
	v_mfma_f32_16x16x32_bf16 v[124:127], v[142:145], v[178:181], v[124:127]
	v_mfma_f32_16x16x32_bf16 v[116:119], v[170:173], v[178:181], v[116:119]
	s_waitcnt lgkmcnt(5)
	v_mfma_f32_16x16x32_bf16 v[112:115], v[218:221], v[178:181], v[112:115]
	v_mfma_f32_16x16x32_bf16 v[120:123], v[210:213], v[178:181], v[120:123]
	s_waitcnt lgkmcnt(3)
	v_mfma_f32_16x16x32_bf16 v[104:107], v[210:213], v[186:189], v[104:107]
	v_mfma_f32_16x16x32_bf16 v[96:99], v[218:221], v[186:189], v[96:99]
	s_waitcnt lgkmcnt(1)
	v_mfma_f32_16x16x32_bf16 v[100:103], v[170:173], v[186:189], v[100:103]
	v_mfma_f32_16x16x32_bf16 v[108:111], v[142:145], v[186:189], v[108:111]
	v_mfma_f32_16x16x32_bf16 v[92:95], v[142:145], v[194:197], v[92:95]
	v_mfma_f32_16x16x32_bf16 v[84:87], v[170:173], v[194:197], v[84:87]
	v_mfma_f32_16x16x32_bf16 v[80:83], v[218:221], v[194:197], v[80:83]
	v_mfma_f32_16x16x32_bf16 v[88:91], v[210:213], v[194:197], v[88:91]
	v_mfma_f32_16x16x32_bf16 v[72:75], v[210:213], v[202:205], v[72:75]
	v_mfma_f32_16x16x32_bf16 v[64:67], v[218:221], v[202:205], v[64:67]
	s_waitcnt lgkmcnt(0)
	v_mfma_f32_16x16x32_bf16 v[68:71], v[170:173], v[202:205], v[68:71]
	v_mfma_f32_16x16x32_bf16 v[76:79], v[142:145], v[202:205], v[76:79]
	s_waitcnt lgkmcnt(3)
	v_mfma_f32_16x16x32_bf16 v[76:79], v[166:169], v[206:209], v[76:79]
	s_waitcnt lgkmcnt(1)
	v_mfma_f32_16x16x32_bf16 v[68:71], v[174:177], v[206:209], v[68:71]
	v_mfma_f32_16x16x32_bf16 v[64:67], v[222:225], v[206:209], v[64:67]
	v_mfma_f32_16x16x32_bf16 v[72:75], v[214:217], v[206:209], v[72:75]
	v_mfma_f32_16x16x32_bf16 v[88:91], v[214:217], v[198:201], v[88:91]
	v_mfma_f32_16x16x32_bf16 v[80:83], v[222:225], v[198:201], v[80:83]
	v_mfma_f32_16x16x32_bf16 v[84:87], v[174:177], v[198:201], v[84:87]
	v_mfma_f32_16x16x32_bf16 v[92:95], v[166:169], v[198:201], v[92:95]
	v_mfma_f32_16x16x32_bf16 v[108:111], v[166:169], v[190:193], v[108:111]
	s_waitcnt lgkmcnt(0)
	v_mfma_f32_16x16x32_bf16 v[100:103], v[174:177], v[190:193], v[100:103]
	v_mfma_f32_16x16x32_bf16 v[96:99], v[222:225], v[190:193], v[96:99]
	v_mfma_f32_16x16x32_bf16 v[104:107], v[214:217], v[190:193], v[104:107]
	v_mfma_f32_16x16x32_bf16 v[120:123], v[214:217], v[182:185], v[120:123]
	v_mfma_f32_16x16x32_bf16 v[112:115], v[222:225], v[182:185], v[112:115]
	v_mfma_f32_16x16x32_bf16 v[116:119], v[174:177], v[182:185], v[116:119]
	v_mfma_f32_16x16x32_bf16 v[124:127], v[166:169], v[182:185], v[124:127]
	s_barrier
; template <int N, int K, int EPI>
; __device__ void gemm_phase(const u16* __restrict__ A, const u16* __restrict__ Bt, const EpiArgs ea, char* smem, int tid) {
;     ...
;       if constexpr (EPI == EPI_SWIGLU) {
;         u16* h = ea.o0;
; #pragma unroll
;         for (int ai = 0; ai < 2; ++ai)
; #pragma unroll
;           for (int m = 0; m < 4; ++m) {
;             const int row = brow + ai * HALF + wr * 64 + m * 16 + fr_e;
;             const int col = pn * 128 + wc * 32 + fq_e * 8;
;             u32x4 o;
; #pragma unroll
;             for (int n = 0; n < 2; ++n) {
;               const f32x4 t4 = acc[ai][0][m][n], u4 = acc[ai][1][m][n];
;               f32x2 tl = {t4[0], t4[1]}, th = {t4[2], t4[3]}, ul = {u4[0], u4[1]}, uh = {u4[2], u4[3]};
;               f32x2 el = {__builtin_amdgcn_exp2f(-t4[0]), __builtin_amdgcn_exp2f(-t4[1])};
;               f32x2 eh = {__builtin_amdgcn_exp2f(-t4[2]), __builtin_amdgcn_exp2f(-t4[3])};
;               el = el + 1.f; eh = eh + 1.f;
;               f32x2 rl = {__builtin_amdgcn_rcpf(el[0]), __builtin_amdgcn_rcpf(el[1])};
;               f32x2 rh = {__builtin_amdgcn_rcpf(eh[0]), __builtin_amdgcn_rcpf(eh[1])};
;               const f32x2 hl = tl * ul * rl, hh2 = th * uh * rh;
	s_or_b32 s70, s70, 64
	s_add_u32 s88, s16, 0x80
	s_addc_u32 s89, s17, 0
	s_add_u32 s16, s16, 0x20080
	s_mov_b32 m0, s31
	s_nop 0
	global_load_lds_dwordx4 v130, s[88:89]
	s_addc_u32 s17, s17, 0
	s_mov_b32 m0, s34
	s_nop 0
	global_load_lds_dwordx4 v130, s[16:17]
	ds_read_b128 v[178:181], v136 offset:49152
	ds_read_b128 v[182:185], v137 offset:49152
	ds_read_b128 v[186:189], v136 offset:51200
	ds_read_b128 v[190:193], v137 offset:51200
	ds_read_b128 v[194:197], v136 offset:53248
	ds_read_b128 v[198:201], v137 offset:53248
	ds_read_b128 v[202:205], v136 offset:55296
	ds_read_b128 v[206:209], v137 offset:55296
	s_add_u32 s16, s18, 0x80
	s_addc_u32 s17, s19, 0
	s_add_u32 s18, s18, 0x20080
	s_mov_b32 m0, s35
	s_nop 0
	global_load_lds_dwordx4 v130, s[16:17]
	s_addc_u32 s19, s19, 0
	s_mov_b32 m0, s36
	s_nop 0
	global_load_lds_dwordx4 v130, s[18:19]
	s_lshl_b64 s[16:17], s[70:71], 1
	s_add_u32 s16, s83, s16
	s_addc_u32 s17, s82, s17
	s_add_u32 s18, s16, 0x20000
	s_mov_b32 m0, s37
	s_nop 0
	global_load_lds_dwordx4 v130, s[16:17]
	s_addc_u32 s19, s17, 0
	s_mov_b32 m0, s42
	s_nop 0
	global_load_lds_dwordx4 v130, s[18:19]
	s_waitcnt vmcnt(8) lgkmcnt(0)
	s_barrier
	s_waitcnt lgkmcnt(7)
	v_mfma_f32_16x16x32_bf16 v[60:63], v[142:145], v[178:181], v[60:63]
	v_mfma_f32_16x16x32_bf16 v[52:55], v[170:173], v[178:181], v[52:55]
	s_waitcnt lgkmcnt(5)
	v_mfma_f32_16x16x32_bf16 v[48:51], v[218:221], v[178:181], v[48:51]
	v_mfma_f32_16x16x32_bf16 v[56:59], v[210:213], v[178:181], v[56:59]
	s_waitcnt lgkmcnt(3)
	v_mfma_f32_16x16x32_bf16 v[40:43], v[210:213], v[186:189], v[40:43]
	v_mfma_f32_16x16x32_bf16 v[32:35], v[218:221], v[186:189], v[32:35]
	s_waitcnt lgkmcnt(1)
	v_mfma_f32_16x16x32_bf16 v[36:39], v[170:173], v[186:189], v[36:39]
	v_mfma_f32_16x16x32_bf16 v[44:47], v[142:145], v[186:189], v[44:47]
	v_mfma_f32_16x16x32_bf16 v[28:31], v[142:145], v[194:197], v[28:31]
	v_mfma_f32_16x16x32_bf16 v[20:23], v[170:173], v[194:197], v[20:23]
	v_mfma_f32_16x16x32_bf16 v[16:19], v[218:221], v[194:197], v[16:19]
	v_mfma_f32_16x16x32_bf16 v[24:27], v[210:213], v[194:197], v[24:27]
	v_mfma_f32_16x16x32_bf16 v[8:11], v[210:213], v[202:205], v[8:11]
	v_mfma_f32_16x16x32_bf16 v[0:3], v[218:221], v[202:205], v[0:3]
	s_waitcnt lgkmcnt(0)
	v_mfma_f32_16x16x32_bf16 v[4:7], v[170:173], v[202:205], v[4:7]
	v_mfma_f32_16x16x32_bf16 v[12:15], v[142:145], v[202:205], v[12:15]
	v_mfma_f32_16x16x32_bf16 v[12:15], v[166:169], v[206:209], v[12:15]
	v_mfma_f32_16x16x32_bf16 v[4:7], v[174:177], v[206:209], v[4:7]
	v_mfma_f32_16x16x32_bf16 v[0:3], v[222:225], v[206:209], v[0:3]
	v_mfma_f32_16x16x32_bf16 v[8:11], v[214:217], v[206:209], v[8:11]
	v_mfma_f32_16x16x32_bf16 v[24:27], v[214:217], v[198:201], v[24:27]
	v_mfma_f32_16x16x32_bf16 v[16:19], v[222:225], v[198:201], v[16:19]
	v_mfma_f32_16x16x32_bf16 v[20:23], v[174:177], v[198:201], v[20:23]
	v_mfma_f32_16x16x32_bf16 v[28:31], v[166:169], v[198:201], v[28:31]
	v_mfma_f32_16x16x32_bf16 v[44:47], v[166:169], v[190:193], v[44:47]
	v_mfma_f32_16x16x32_bf16 v[36:39], v[174:177], v[190:193], v[36:39]
	v_mfma_f32_16x16x32_bf16 v[32:35], v[222:225], v[190:193], v[32:35]
	v_mfma_f32_16x16x32_bf16 v[40:43], v[214:217], v[190:193], v[40:43]
	v_mfma_f32_16x16x32_bf16 v[56:59], v[214:217], v[182:185], v[56:59]
	v_mfma_f32_16x16x32_bf16 v[48:51], v[222:225], v[182:185], v[48:51]
	v_mfma_f32_16x16x32_bf16 v[52:55], v[174:177], v[182:185], v[52:55]
	v_mfma_f32_16x16x32_bf16 v[60:63], v[166:169], v[182:185], v[60:63]
	s_add_i32 s3, s3, 2
	s_addk_i32 s5, 0x80
	s_add_u32 s14, s14, 0x100
	s_addc_u32 s15, s15, 0
	s_cmp_gt_u32 s3, 13
	s_barrier
	s_cbranch_scc0 .LBB0_236
	v_exp_f32_e64 v144, -v124
	v_exp_f32_e64 v145, -v125
	v_exp_f32_e64 v146, -v126
	v_exp_f32_e64 v147, -v127
	v_pk_mul_f32 v[122:123], v[126:127], v[122:123]
	v_pk_add_f32 v[144:145], v[144:145], 1.0 op_sel_hi:[1,0]
	v_pk_mul_f32 v[120:121], v[124:125], v[120:121]
	v_pk_add_f32 v[146:147], v[146:147], 1.0 op_sel_hi:[1,0]
	v_rcp_f32_e32 v144, v144
	v_rcp_f32_e32 v145, v145
	v_rcp_f32_e32 v146, v146
	v_rcp_f32_e32 v147, v147
	v_exp_f32_e64 v124, -v116
	v_exp_f32_e64 v125, -v117
	v_exp_f32_e64 v126, -v118
	v_exp_f32_e64 v127, -v119
	v_pk_mul_f32 v[120:121], v[144:145], v[120:121]
	v_pk_mul_f32 v[122:123], v[146:147], v[122:123]
	v_cvt_pk_bf16_f32 v120, v120, v121
	v_pk_mul_f32 v[114:115], v[118:119], v[114:115]
	v_cvt_pk_bf16_f32 v121, v122, v123
	v_pk_add_f32 v[122:123], v[124:125], 1.0 op_sel_hi:[1,0]
	v_pk_add_f32 v[124:125], v[126:127], 1.0 op_sel_hi:[1,0]
	v_rcp_f32_e32 v122, v122
	v_rcp_f32_e32 v123, v123
	v_rcp_f32_e32 v124, v124
	v_rcp_f32_e32 v125, v125
	v_pk_mul_f32 v[112:113], v[116:117], v[112:113]
	v_pk_mul_f32 v[106:107], v[110:111], v[106:107]
	v_pk_mul_f32 v[112:113], v[122:123], v[112:113]
	v_pk_mul_f32 v[114:115], v[124:125], v[114:115]
	v_cvt_pk_bf16_f32 v122, v112, v113
	v_exp_f32_e64 v112, -v108
	v_cvt_pk_bf16_f32 v123, v114, v115
	v_exp_f32_e64 v113, -v109
	v_exp_f32_e64 v114, -v110
	v_exp_f32_e64 v115, -v111
	v_pk_mul_f32 v[104:105], v[108:109], v[104:105]
	v_pk_add_f32 v[112:113], v[112:113], 1.0 op_sel_hi:[1,0]
	v_exp_f32_e64 v108, -v100
	v_pk_add_f32 v[114:115], v[114:115], 1.0 op_sel_hi:[1,0]
	v_rcp_f32_e32 v112, v112
	v_rcp_f32_e32 v113, v113
	v_rcp_f32_e32 v114, v114
	v_rcp_f32_e32 v115, v115
	v_exp_f32_e64 v109, -v101
	v_exp_f32_e64 v110, -v102
	v_exp_f32_e64 v111, -v103
	v_pk_mul_f32 v[104:105], v[112:113], v[104:105]
	v_pk_mul_f32 v[106:107], v[114:115], v[106:107]
	v_cvt_pk_bf16_f32 v104, v104, v105
	v_pk_mul_f32 v[98:99], v[102:103], v[98:99]
	v_cvt_pk_bf16_f32 v105, v106, v107
	v_pk_add_f32 v[106:107], v[108:109], 1.0 op_sel_hi:[1,0]
; template <int N, int K, int EPI>
; __device__ void gemm_phase(const u16* __restrict__ A, const u16* __restrict__ Bt, const EpiArgs ea, char* smem, int tid) {
;     ...
;         for (int ai = 0; ai < 2; ++ai)
; #pragma unroll
;           for (int m = 0; m < 4; ++m) {
;             const int row = brow + ai * HALF + wr * 64 + m * 16 + fr_e;
;             const int col = pn * 128 + wc * 32 + fq_e * 8;
;             u32x4 o;
; #pragma unroll
;             for (int n = 0; n < 2; ++n) {
;               const f32x4 t4 = acc[ai][0][m][n], u4 = acc[ai][1][m][n];
;               f32x2 tl = {t4[0], t4[1]}, th = {t4[2], t4[3]}, ul = {u4[0], u4[1]}, uh = {u4[2], u4[3]};
;               f32x2 el = {__builtin_amdgcn_exp2f(-t4[0]), __builtin_amdgcn_exp2f(-t4[1])};
;               f32x2 eh = {__builtin_amdgcn_exp2f(-t4[2]), __builtin_amdgcn_exp2f(-t4[3])};
;               el = el + 1.f; eh = eh + 1.f;
;               f32x2 rl = {__builtin_amdgcn_rcpf(el[0]), __builtin_amdgcn_rcpf(el[1])};
;               f32x2 rh = {__builtin_amdgcn_rcpf(eh[0]), __builtin_amdgcn_rcpf(eh[1])};
;               const f32x2 hl = tl * ul * rl, hh2 = th * uh * rh;
;               o[2 * n] = pk_bf16(hl[0], hl[1]); o[2 * n + 1] = pk_bf16(hh2[0], hh2[1]);
;             }
;             *(u32x4*)(h + (size_t)row * FF + col) = o;
	v_pk_add_f32 v[108:109], v[110:111], 1.0 op_sel_hi:[1,0]
	v_rcp_f32_e32 v106, v106
	v_rcp_f32_e32 v107, v107
	v_rcp_f32_e32 v108, v108
	v_rcp_f32_e32 v109, v109
	v_pk_mul_f32 v[96:97], v[100:101], v[96:97]
	v_pk_mul_f32 v[90:91], v[94:95], v[90:91]
	v_pk_mul_f32 v[96:97], v[106:107], v[96:97]
	v_pk_mul_f32 v[98:99], v[108:109], v[98:99]
	v_cvt_pk_bf16_f32 v106, v96, v97
	v_exp_f32_e64 v96, -v92
	v_cvt_pk_bf16_f32 v107, v98, v99
	v_exp_f32_e64 v97, -v93
	v_exp_f32_e64 v98, -v94
	v_exp_f32_e64 v99, -v95
	v_pk_mul_f32 v[88:89], v[92:93], v[88:89]
	v_pk_add_f32 v[96:97], v[96:97], 1.0 op_sel_hi:[1,0]
	v_exp_f32_e64 v92, -v84
	v_pk_add_f32 v[98:99], v[98:99], 1.0 op_sel_hi:[1,0]
	v_rcp_f32_e32 v96, v96
	v_rcp_f32_e32 v97, v97
	v_rcp_f32_e32 v98, v98
	v_rcp_f32_e32 v99, v99
	v_exp_f32_e64 v93, -v85
	v_exp_f32_e64 v94, -v86
	v_exp_f32_e64 v95, -v87
	v_pk_mul_f32 v[88:89], v[96:97], v[88:89]
	v_pk_mul_f32 v[90:91], v[98:99], v[90:91]
	v_cvt_pk_bf16_f32 v88, v88, v89
	v_pk_mul_f32 v[82:83], v[86:87], v[82:83]
	v_cvt_pk_bf16_f32 v89, v90, v91
	v_pk_add_f32 v[90:91], v[92:93], 1.0 op_sel_hi:[1,0]
	v_pk_add_f32 v[92:93], v[94:95], 1.0 op_sel_hi:[1,0]
	v_rcp_f32_e32 v90, v90
	v_rcp_f32_e32 v91, v91
	v_rcp_f32_e32 v92, v92
	v_rcp_f32_e32 v93, v93
	v_pk_mul_f32 v[80:81], v[84:85], v[80:81]
	v_pk_mul_f32 v[74:75], v[78:79], v[74:75]
	v_pk_mul_f32 v[80:81], v[90:91], v[80:81]
	v_pk_mul_f32 v[82:83], v[92:93], v[82:83]
	v_cvt_pk_bf16_f32 v90, v80, v81
	v_exp_f32_e64 v80, -v76
	v_cvt_pk_bf16_f32 v91, v82, v83
	v_exp_f32_e64 v81, -v77
	v_exp_f32_e64 v82, -v78
	v_exp_f32_e64 v83, -v79
	v_pk_mul_f32 v[72:73], v[76:77], v[72:73]
	v_pk_add_f32 v[80:81], v[80:81], 1.0 op_sel_hi:[1,0]
	v_exp_f32_e64 v76, -v68
	v_pk_add_f32 v[82:83], v[82:83], 1.0 op_sel_hi:[1,0]
	v_rcp_f32_e32 v80, v80
	v_rcp_f32_e32 v81, v81
	v_rcp_f32_e32 v82, v82
	v_rcp_f32_e32 v83, v83
	v_exp_f32_e64 v77, -v69
	v_exp_f32_e64 v78, -v70
	v_exp_f32_e64 v79, -v71
	v_pk_mul_f32 v[72:73], v[80:81], v[72:73]
	v_pk_mul_f32 v[74:75], v[82:83], v[74:75]
	v_cvt_pk_bf16_f32 v72, v72, v73
	s_lshl_b32 s3, s77, 8
	v_cvt_pk_bf16_f32 v73, v74, v75
	v_pk_add_f32 v[74:75], v[76:77], 1.0 op_sel_hi:[1,0]
	v_pk_add_f32 v[76:77], v[78:79], 1.0 op_sel_hi:[1,0]
	v_rcp_f32_e32 v74, v74
	v_rcp_f32_e32 v76, v76
	v_rcp_f32_e32 v77, v77
	v_rcp_f32_e32 v75, v75
	v_mov_b32_e32 v128, v132
	v_mov_b32_e32 v129, v131
	s_add_i32 s3, s3, s43
	v_pk_mul_f32 v[66:67], v[70:71], v[66:67]
	v_add_u32_e32 v142, s3, v129
	s_lshl_b32 s3, s73, 7
	s_or_b32 s3, s3, s66
	v_pk_mul_f32 v[64:65], v[68:69], v[64:65]
	v_pk_mul_f32 v[66:67], v[76:77], v[66:67]
	v_lshl_add_u32 v128, v128, 3, s3
	v_pk_mul_f32 v[64:65], v[74:75], v[64:65]
	v_cvt_pk_bf16_f32 v75, v66, v67
	v_exp_f32_e64 v66, -v60
	v_exp_f32_e64 v67, -v61
	v_exp_f32_e64 v68, -v62
	v_exp_f32_e64 v69, -v63
	v_ashrrev_i32_e32 v129, 31, v128
	v_lshl_add_u64 v[128:129], v[128:129], 1, s[80:81]
	v_cvt_pk_bf16_f32 v74, v64, v65
	v_add_u32_e32 v64, 48, v142
	v_mad_i64_i32 v[64:65], s[10:11], v64, s68, v[128:129]
	global_store_dwordx4 v[64:65], v[72:75], off
	v_pk_add_f32 v[64:65], v[66:67], 1.0 op_sel_hi:[1,0]
	v_pk_add_f32 v[66:67], v[68:69], 1.0 op_sel_hi:[1,0]
	v_rcp_f32_e32 v64, v64
	v_rcp_f32_e32 v65, v65
	v_rcp_f32_e32 v66, v66
	v_rcp_f32_e32 v67, v67
	v_pk_mul_f32 v[58:59], v[62:63], v[58:59]
	v_pk_mul_f32 v[56:57], v[60:61], v[56:57]
	v_exp_f32_e64 v60, -v52
	v_exp_f32_e64 v61, -v53
	v_exp_f32_e64 v62, -v54
	v_exp_f32_e64 v63, -v55
	v_pk_mul_f32 v[56:57], v[64:65], v[56:57]
	v_pk_mul_f32 v[58:59], v[66:67], v[58:59]
	v_cvt_pk_bf16_f32 v56, v56, v57
	v_pk_mul_f32 v[50:51], v[54:55], v[50:51]
	v_cvt_pk_bf16_f32 v57, v58, v59
	v_pk_add_f32 v[58:59], v[60:61], 1.0 op_sel_hi:[1,0]
	v_pk_add_f32 v[60:61], v[62:63], 1.0 op_sel_hi:[1,0]
	v_rcp_f32_e32 v58, v58
	v_rcp_f32_e32 v59, v59
	v_rcp_f32_e32 v60, v60
	v_rcp_f32_e32 v61, v61
	v_pk_mul_f32 v[48:49], v[52:53], v[48:49]
	v_pk_mul_f32 v[42:43], v[46:47], v[42:43]
	v_pk_mul_f32 v[48:49], v[58:59], v[48:49]
	v_pk_mul_f32 v[50:51], v[60:61], v[50:51]
	v_cvt_pk_bf16_f32 v58, v48, v49
	v_exp_f32_e64 v48, -v44
	v_cvt_pk_bf16_f32 v59, v50, v51
	v_exp_f32_e64 v49, -v45
	v_exp_f32_e64 v50, -v46
	v_exp_f32_e64 v51, -v47
	v_pk_mul_f32 v[40:41], v[44:45], v[40:41]
; #define WAIT_V(n) asm volatile("s_waitcnt vmcnt(" #n ")" ::: "memory")
; #define BAR __builtin_amdgcn_s_barrier()
; template <int N, int K, int EPI>
; __device__ void gemm_phase(const u16* __restrict__ A, const u16* __restrict__ Bt, const EpiArgs ea, char* smem, int tid) {
;     ...
;         for (int ai = 0; ai < 2; ++ai)
; #pragma unroll
;           for (int m = 0; m < 4; ++m) {
;             const int row = brow + ai * HALF + wr * 64 + m * 16 + fr_e;
;             const int col = pn * 128 + wc * 32 + fq_e * 8;
;             u32x4 o;
; #pragma unroll
;             for (int n = 0; n < 2; ++n) {
;               const f32x4 t4 = acc[ai][0][m][n], u4 = acc[ai][1][m][n];
;               f32x2 tl = {t4[0], t4[1]}, th = {t4[2], t4[3]}, ul = {u4[0], u4[1]}, uh = {u4[2], u4[3]};
;               f32x2 el = {__builtin_amdgcn_exp2f(-t4[0]), __builtin_amdgcn_exp2f(-t4[1])};
;               f32x2 eh = {__builtin_amdgcn_exp2f(-t4[2]), __builtin_amdgcn_exp2f(-t4[3])};
;               el = el + 1.f; eh = eh + 1.f;
;               f32x2 rl = {__builtin_amdgcn_rcpf(el[0]), __builtin_amdgcn_rcpf(el[1])};
;               f32x2 rh = {__builtin_amdgcn_rcpf(eh[0]), __builtin_amdgcn_rcpf(eh[1])};
;               const f32x2 hl = tl * ul * rl, hh2 = th * uh * rh;
;               o[2 * n] = pk_bf16(hl[0], hl[1]); o[2 * n + 1] = pk_bf16(hh2[0], hh2[1]);
;             }
;             *(u32x4*)(h + (size_t)row * FF + col) = o;
;     ...
;     if (!has_next) break;
; #pragma unroll
;     for (int ai = 0; ai < 2; ++ai)
; #pragma unroll
;       for (int bj = 0; bj < 2; ++bj)
; #pragma unroll
;         for (int m = 0; m < 4; ++m)
; #pragma unroll
;           for (int n = 0; n < 2; ++n) acc[ai][bj][m][n] = f32x4{0.f, 0.f, 0.f, 0.f};
;     v = vn; pm = pmn; pn = pnn; Ab = Abn; Bb = Bbn;
;   }
;   WAIT_V(0);
;   if (wr == 0) BAR;
	v_pk_add_f32 v[48:49], v[48:49], 1.0 op_sel_hi:[1,0]
	v_exp_f32_e64 v44, -v36
	v_pk_add_f32 v[50:51], v[50:51], 1.0 op_sel_hi:[1,0]
	v_rcp_f32_e32 v48, v48
	v_rcp_f32_e32 v49, v49
	v_rcp_f32_e32 v50, v50
	v_rcp_f32_e32 v51, v51
	v_exp_f32_e64 v45, -v37
	v_exp_f32_e64 v46, -v38
	v_exp_f32_e64 v47, -v39
	v_pk_mul_f32 v[40:41], v[48:49], v[40:41]
	v_pk_mul_f32 v[42:43], v[50:51], v[42:43]
	v_cvt_pk_bf16_f32 v40, v40, v41
	v_pk_mul_f32 v[34:35], v[38:39], v[34:35]
	v_cvt_pk_bf16_f32 v41, v42, v43
	v_pk_add_f32 v[42:43], v[44:45], 1.0 op_sel_hi:[1,0]
	v_pk_add_f32 v[44:45], v[46:47], 1.0 op_sel_hi:[1,0]
	v_rcp_f32_e32 v42, v42
	v_rcp_f32_e32 v43, v43
	v_rcp_f32_e32 v44, v44
	v_rcp_f32_e32 v45, v45
	v_pk_mul_f32 v[32:33], v[36:37], v[32:33]
	v_pk_mul_f32 v[26:27], v[30:31], v[26:27]
	v_pk_mul_f32 v[32:33], v[42:43], v[32:33]
	v_pk_mul_f32 v[34:35], v[44:45], v[34:35]
	v_cvt_pk_bf16_f32 v42, v32, v33
	v_exp_f32_e64 v32, -v28
	v_cvt_pk_bf16_f32 v43, v34, v35
	v_exp_f32_e64 v33, -v29
	v_exp_f32_e64 v34, -v30
	v_exp_f32_e64 v35, -v31
	v_pk_mul_f32 v[24:25], v[28:29], v[24:25]
	v_pk_add_f32 v[32:33], v[32:33], 1.0 op_sel_hi:[1,0]
	v_exp_f32_e64 v28, -v20
	v_pk_add_f32 v[34:35], v[34:35], 1.0 op_sel_hi:[1,0]
	v_rcp_f32_e32 v32, v32
	v_rcp_f32_e32 v33, v33
	v_rcp_f32_e32 v34, v34
	v_rcp_f32_e32 v35, v35
	v_exp_f32_e64 v29, -v21
	v_exp_f32_e64 v30, -v22
	v_exp_f32_e64 v31, -v23
	v_pk_mul_f32 v[24:25], v[32:33], v[24:25]
	v_pk_mul_f32 v[26:27], v[34:35], v[26:27]
	v_cvt_pk_bf16_f32 v24, v24, v25
	v_pk_mul_f32 v[18:19], v[22:23], v[18:19]
	v_cvt_pk_bf16_f32 v25, v26, v27
	v_pk_add_f32 v[26:27], v[28:29], 1.0 op_sel_hi:[1,0]
	v_pk_add_f32 v[28:29], v[30:31], 1.0 op_sel_hi:[1,0]
	v_rcp_f32_e32 v26, v26
	v_rcp_f32_e32 v27, v27
	v_rcp_f32_e32 v28, v28
	v_rcp_f32_e32 v29, v29
	v_pk_mul_f32 v[16:17], v[20:21], v[16:17]
	v_pk_mul_f32 v[8:9], v[12:13], v[8:9]
	v_pk_mul_f32 v[16:17], v[26:27], v[16:17]
	v_pk_mul_f32 v[18:19], v[28:29], v[18:19]
	v_cvt_pk_bf16_f32 v26, v16, v17
	v_exp_f32_e64 v16, -v12
	v_cvt_pk_bf16_f32 v27, v18, v19
	v_exp_f32_e64 v17, -v13
	v_exp_f32_e64 v18, -v14
	v_exp_f32_e64 v19, -v15
	v_exp_f32_e64 v12, -v4
	v_pk_add_f32 v[16:17], v[16:17], 1.0 op_sel_hi:[1,0]
	v_exp_f32_e64 v13, -v5
	v_pk_add_f32 v[18:19], v[18:19], 1.0 op_sel_hi:[1,0]
	v_rcp_f32_e32 v16, v16
	v_rcp_f32_e32 v17, v17
	v_rcp_f32_e32 v18, v18
	v_rcp_f32_e32 v19, v19
	v_pk_mul_f32 v[10:11], v[14:15], v[10:11]
	v_pk_mul_f32 v[8:9], v[16:17], v[8:9]
	v_exp_f32_e64 v14, -v6
	v_pk_mul_f32 v[10:11], v[18:19], v[10:11]
	v_exp_f32_e64 v15, -v7
	v_cvt_pk_bf16_f32 v8, v8, v9
	v_cvt_pk_bf16_f32 v9, v10, v11
	v_pk_add_f32 v[10:11], v[12:13], 1.0 op_sel_hi:[1,0]
	v_pk_add_f32 v[12:13], v[14:15], 1.0 op_sel_hi:[1,0]
	v_rcp_f32_e32 v10, v10
	v_rcp_f32_e32 v11, v11
	v_pk_mul_f32 v[0:1], v[4:5], v[0:1]
	v_rcp_f32_e32 v12, v12
	v_rcp_f32_e32 v13, v13
	v_pk_mul_f32 v[0:1], v[10:11], v[0:1]
	v_add_u32_e32 v100, 16, v142
	v_add_u32_e32 v84, 32, v142
	v_add_u32_e32 v70, 0x80, v142
	v_add_u32_e32 v36, 0x90, v142
	v_add_u32_e32 v20, 0xa0, v142
	v_cvt_pk_bf16_f32 v10, v0, v1
	v_add_u32_e32 v0, 0xb0, v142
	v_mad_i64_i32 v[116:117], s[10:11], v142, s68, v[128:129]
	v_mad_i64_i32 v[100:101], s[10:11], v100, s68, v[128:129]
	v_mad_i64_i32 v[84:85], s[10:11], v84, s68, v[128:129]
	v_mad_i64_i32 v[52:53], s[10:11], v70, s68, v[128:129]
	v_mad_i64_i32 v[36:37], s[10:11], v36, s68, v[128:129]
	v_mad_i64_i32 v[20:21], s[10:11], v20, s68, v[128:129]
	v_mad_i64_i32 v[0:1], s[10:11], v0, s68, v[128:129]
	v_pk_mul_f32 v[2:3], v[6:7], v[2:3]
	s_and_b64 vcc, exec, s[0:1]
	s_mov_b32 s77, s2
	s_mov_b32 s73, s4
	s_mov_b64 s[12:13], s[8:9]
	s_mov_b64 s[10:11], s[6:7]
	global_store_dwordx4 v[116:117], v[120:123], off
	global_store_dwordx4 v[100:101], v[104:107], off
	global_store_dwordx4 v[84:85], v[88:91], off
	global_store_dwordx4 v[52:53], v[56:59], off
	global_store_dwordx4 v[36:37], v[40:43], off
	global_store_dwordx4 v[20:21], v[24:27], off
	v_pk_mul_f32 v[2:3], v[12:13], v[2:3]
	s_nop 0
	v_cvt_pk_bf16_f32 v11, v2, v3
	global_store_dwordx4 v[0:1], v[8:11], off
	s_cbranch_vccz .LBB0_233
	s_setprio 0
	s_waitcnt vmcnt(0)
	v_readlane_b32 s36, v226, 30
	s_cmpk_gt_u32 s22, 0xff
	s_mov_b64 s[34:35], s[96:97]
	v_readlane_b32 s37, v226, 31
	s_cbranch_scc1 .LBB0_240
	s_barrier
